# in-GEMM leading half with a successor: next unit's header + first load segment run before the realign barrier (idle time), epilogue temporaries renamed off the fragment registers, then straight to the
# speedup vs baseline: 1.0027x; 1.0027x over previous
.Lpre_0:
	s_mov_b32 s98, s65
	s_mov_b32 s100, s36
	s_mov_b32 s65, s10
	s_mov_b32 s36, s12
	s_mov_b64 s[46:47], s[30:31]
	s_mov_b64 s[44:45], s[24:25]
	s_add_i32 s59, s59, 1
	s_mul_i32 s4, s59, s21
	s_mul_hi_u32 s5, s59, s20
	s_add_i32 s5, s5, s4
	s_mul_i32 s4, s59, s20
	s_add_u32 s24, s4, s2
	s_addc_u32 s25, s5, s3
	v_cmp_gt_i64_e32 vcc, s[24:25], v[138:139]
	v_cmp_lt_i64_e64 s[4:5], s[24:25], v[136:137]
	s_cbranch_vccnz .LBB0_183_pk0
	s_lshr_b32 s10, s24, 3
	s_and_b32 s12, s24, 7
	s_lshl_b32 s12, s12, 1
	s_cmp_ge_u32 s10, 0xb0
	s_cbranch_scc0 .Ldec_0_pk0
	s_sub_u32 s10, s10, 0xb0
	s_add_u32 s12, s12, 1

.LBB0_183_pk0:
	s_ashr_i32 s13, s12, 31
	s_lshl_b64 s[24:25], s[12:13], 19
	s_add_u32 s24, s80, s24
	s_addc_u32 s25, s81, s25
	s_and_b64 s[30:31], s[4:5], exec
	s_cselect_b32 s13, s25, s45
	s_cselect_b32 s66, s24, s44
	s_ashr_i32 s11, s10, 31
	s_lshl_b64 s[30:31], s[10:11], 19
	s_add_u32 s30, s52, s30
	s_addc_u32 s31, s53, s31
	s_and_b64 s[48:49], s[4:5], exec
	s_cselect_b32 s11, s31, s47
	s_cselect_b32 s67, s30, s46
	s_add_u32 s44, s44, 0x40080
	s_addc_u32 s45, s45, 0
	s_add_u32 s68, s46, 0x100
	s_addc_u32 s69, s47, 0
	s_mov_b32 s70, -2
	ds_read_b128 v[140:143], v147
	ds_read_b128 v[150:153], v147 offset:1024
	ds_read_b128 v[154:157], v147 offset:2048
	ds_read_b128 v[158:161], v147 offset:3072
	ds_read_b128 v[162:165], v148
	ds_read_b128 v[166:169], v148 offset:1024
	ds_read_b128 v[170:173], v148 offset:2048
	ds_read_b128 v[174:177], v148 offset:3072
	s_add_u32 s18, s44, 0xfffc0080
	s_addc_u32 s19, s45, -1
	s_cmp_eq_u32 s70, 12
	s_cselect_b32 s49, s13, s19
	s_cselect_b32 s48, s66, s18
	s_cselect_b32 s47, s11, s69
	s_cselect_b32 s46, s67, s68
	v_lshl_add_u64 v[178:179], s[44:45], 0, v[132:133]
	s_add_i32 m0, s37, 0xc000
	ds_read_b128 v[184:187], v149
	ds_read_b128 v[188:191], v149 offset:1024
	ds_read_b128 v[192:195], v149 offset:2048
	ds_read_b128 v[196:199], v149 offset:3072
	ds_read_b128 v[200:203], v149 offset:4096
	ds_read_b128 v[204:207], v149 offset:5120
	ds_read_b128 v[208:211], v149 offset:6144
	ds_read_b128 v[212:215], v149 offset:7168
	global_load_lds_dwordx4 v[178:179], off
	v_lshl_add_u64 v[178:179], s[44:45], 0, v[134:135]
	s_add_i32 m0, s37, 0xe000
	s_nop 0
	global_load_lds_dwordx4 v[178:179], off
	s_barrier
	v_mul_f32_e32 v221, 0xbfb8aa3b, v124
	v_exp_f32_e32 v221, v221
	v_mul_f32_e32 v224, 0xbfb8aa3b, v125
	v_exp_f32_e32 v224, v224
	v_lshl_or_b32 v218, s98, 7, v146
	v_add_f32_e32 v221, 1.0, v221
	v_rcp_f32_e32 v221, v221
	v_lshl_add_u32 v220, s100, 8, v144
	v_ashrrev_i32_e32 v219, 31, v218
	v_mov_b64_e32 v[216:217], s[22:23]
	v_mul_f32_e32 v124, v124, v221
	v_mul_f32_e32 v120, v120, v124
	v_add_f32_e32 v124, 1.0, v224
	v_mul_f32_e32 v221, 0xbfb8aa3b, v126
	v_rcp_f32_e32 v124, v124
	v_exp_f32_e32 v221, v221
	v_mul_f32_e32 v224, 0xbfb8aa3b, v127
	v_exp_f32_e32 v224, v224
	v_mul_f32_e32 v124, v125, v124
	v_add_f32_e32 v125, 1.0, v221
	v_rcp_f32_e32 v125, v125
	v_add_f32_e32 v221, 1.0, v224
	v_rcp_f32_e32 v221, v221
	v_mul_f32_e32 v121, v121, v124
	v_mul_f32_e32 v124, v126, v125
	v_mul_f32_e32 v125, 0xbfb8aa3b, v116
	v_exp_f32_e32 v125, v125
	v_mul_f32_e32 v122, v122, v124
	v_mul_f32_e32 v124, v127, v221
	v_mul_f32_e32 v123, v123, v124
	v_cvt_pk_bf16_f32 v120, v120, v121
	v_cvt_pk_bf16_f32 v121, v122, v123
	v_add_f32_e32 v122, 1.0, v125
	v_rcp_f32_e32 v122, v122
	v_mul_f32_e32 v123, 0xbfb8aa3b, v117
	v_exp_f32_e32 v123, v123
	v_mad_i64_i32 v[222:223], vcc, v220, s64, v[216:217]
	v_lshlrev_b64 v[218:219], 1, v[218:219]
	v_lshl_add_u64 v[222:223], v[222:223], 0, v[218:219]
	v_mul_f32_e32 v116, v116, v122
	global_store_dwordx2 v[222:223], v[120:121], off
	v_mul_f32_e32 v112, v112, v116
	v_add_f32_e32 v116, 1.0, v123
	v_mul_f32_e32 v120, 0xbfb8aa3b, v118
	v_rcp_f32_e32 v116, v116
	v_exp_f32_e32 v120, v120
	v_mul_f32_e32 v121, 0xbfb8aa3b, v119
	v_exp_f32_e32 v121, v121
	v_mul_f32_e32 v116, v117, v116
	v_add_f32_e32 v117, 1.0, v120
	v_rcp_f32_e32 v117, v117
	v_add_f32_e32 v120, 1.0, v121
	v_rcp_f32_e32 v120, v120
	v_mul_f32_e32 v113, v113, v116
	v_mul_f32_e32 v116, v118, v117
	v_mul_f32_e32 v114, v114, v116
	v_mul_f32_e32 v116, v119, v120
	v_cvt_pk_bf16_f32 v112, v112, v113
	v_mul_f32_e32 v115, v115, v116
	v_cvt_pk_bf16_f32 v113, v114, v115
	global_store_dwordx2 v[222:223], v[112:113], off offset:128
	v_mul_f32_e32 v112, 0xbfb8aa3b, v108
	v_exp_f32_e32 v114, v112
	v_mul_f32_e32 v115, 0xbfb8aa3b, v109
	v_exp_f32_e32 v115, v115
	v_or_b32_e32 v112, 16, v220
	v_add_f32_e32 v114, 1.0, v114
	v_rcp_f32_e32 v114, v114
	v_mad_i64_i32 v[112:113], vcc, v112, s64, v[216:217]
	v_lshl_add_u64 v[112:113], v[112:113], 0, v[218:219]
	v_mul_f32_e32 v108, v108, v114
	v_mul_f32_e32 v104, v104, v108
	v_add_f32_e32 v108, 1.0, v115
	v_mul_f32_e32 v114, 0xbfb8aa3b, v110
	v_rcp_f32_e32 v108, v108
	v_exp_f32_e32 v114, v114
	v_mul_f32_e32 v115, 0xbfb8aa3b, v111
	v_exp_f32_e32 v115, v115
	v_mul_f32_e32 v108, v109, v108
	v_add_f32_e32 v109, 1.0, v114
	v_rcp_f32_e32 v109, v109
	v_add_f32_e32 v114, 1.0, v115
	v_rcp_f32_e32 v114, v114
	v_mul_f32_e32 v105, v105, v108
	v_mul_f32_e32 v108, v110, v109
	v_mul_f32_e32 v109, 0xbfb8aa3b, v100
	v_exp_f32_e32 v109, v109
	v_mul_f32_e32 v106, v106, v108
	v_mul_f32_e32 v108, v111, v114
	v_mul_f32_e32 v107, v107, v108
	v_cvt_pk_bf16_f32 v104, v104, v105
	v_cvt_pk_bf16_f32 v105, v106, v107
	v_add_f32_e32 v106, 1.0, v109
	v_rcp_f32_e32 v106, v106
	v_mul_f32_e32 v107, 0xbfb8aa3b, v101
	v_exp_f32_e32 v107, v107
	global_store_dwordx2 v[112:113], v[104:105], off
	v_mul_f32_e32 v100, v100, v106
	v_mul_f32_e32 v96, v96, v100
	v_add_f32_e32 v100, 1.0, v107
	v_mul_f32_e32 v104, 0xbfb8aa3b, v102
	v_rcp_f32_e32 v100, v100
	v_exp_f32_e32 v104, v104
	v_mul_f32_e32 v105, 0xbfb8aa3b, v103
	v_exp_f32_e32 v105, v105
	v_mul_f32_e32 v100, v101, v100
	v_add_f32_e32 v101, 1.0, v104
	v_rcp_f32_e32 v101, v101
	v_add_f32_e32 v104, 1.0, v105
	v_rcp_f32_e32 v104, v104
	v_mul_f32_e32 v97, v97, v100
	v_mul_f32_e32 v100, v102, v101
	v_mul_f32_e32 v98, v98, v100
	v_mul_f32_e32 v100, v103, v104
	v_cvt_pk_bf16_f32 v96, v96, v97
	v_mul_f32_e32 v99, v99, v100
	v_cvt_pk_bf16_f32 v97, v98, v99
	global_store_dwordx2 v[112:113], v[96:97], off offset:128
	v_mul_f32_e32 v96, 0xbfb8aa3b, v92
	v_exp_f32_e32 v98, v96
	v_mul_f32_e32 v99, 0xbfb8aa3b, v93
	v_exp_f32_e32 v99, v99
	v_or_b32_e32 v96, 32, v220
	v_add_f32_e32 v98, 1.0, v98
	v_rcp_f32_e32 v98, v98
	v_mad_i64_i32 v[96:97], vcc, v96, s64, v[216:217]
	v_lshl_add_u64 v[96:97], v[96:97], 0, v[218:219]
	v_mul_f32_e32 v92, v92, v98
	v_mul_f32_e32 v88, v88, v92
	v_add_f32_e32 v92, 1.0, v99
	v_mul_f32_e32 v98, 0xbfb8aa3b, v94
	v_rcp_f32_e32 v92, v92
	v_exp_f32_e32 v98, v98
	v_mul_f32_e32 v99, 0xbfb8aa3b, v95
	v_exp_f32_e32 v99, v99
	v_mul_f32_e32 v92, v93, v92
	v_add_f32_e32 v93, 1.0, v98
	v_rcp_f32_e32 v93, v93
	v_add_f32_e32 v98, 1.0, v99
	v_rcp_f32_e32 v98, v98
	v_mul_f32_e32 v89, v89, v92
	v_mul_f32_e32 v92, v94, v93
	v_mul_f32_e32 v93, 0xbfb8aa3b, v84
	v_exp_f32_e32 v93, v93
	v_mul_f32_e32 v90, v90, v92
	v_mul_f32_e32 v92, v95, v98
	v_mul_f32_e32 v91, v91, v92
	v_cvt_pk_bf16_f32 v88, v88, v89
	v_cvt_pk_bf16_f32 v89, v90, v91
	v_add_f32_e32 v90, 1.0, v93
	v_rcp_f32_e32 v90, v90
	v_mul_f32_e32 v91, 0xbfb8aa3b, v85
	v_exp_f32_e32 v91, v91
	global_store_dwordx2 v[96:97], v[88:89], off
	v_mul_f32_e32 v84, v84, v90
	v_mul_f32_e32 v80, v80, v84
	v_add_f32_e32 v84, 1.0, v91
	v_mul_f32_e32 v88, 0xbfb8aa3b, v86
	v_rcp_f32_e32 v84, v84
	v_exp_f32_e32 v88, v88
	v_mul_f32_e32 v89, 0xbfb8aa3b, v87
	v_exp_f32_e32 v89, v89
	v_mul_f32_e32 v84, v85, v84
	v_add_f32_e32 v85, 1.0, v88
	v_rcp_f32_e32 v85, v85
	v_add_f32_e32 v88, 1.0, v89
	v_rcp_f32_e32 v88, v88
	v_mul_f32_e32 v81, v81, v84
	v_mul_f32_e32 v84, v86, v85
	v_mul_f32_e32 v82, v82, v84
	v_mul_f32_e32 v84, v87, v88
	v_cvt_pk_bf16_f32 v80, v80, v81
	v_mul_f32_e32 v83, v83, v84
	v_cvt_pk_bf16_f32 v81, v82, v83
	global_store_dwordx2 v[96:97], v[80:81], off offset:128
	v_mul_f32_e32 v80, 0xbfb8aa3b, v76
	v_exp_f32_e32 v82, v80
	v_mul_f32_e32 v83, 0xbfb8aa3b, v77
	v_exp_f32_e32 v83, v83
	v_or_b32_e32 v80, 48, v220
	v_add_f32_e32 v82, 1.0, v82
	v_rcp_f32_e32 v82, v82
	v_mad_i64_i32 v[80:81], vcc, v80, s64, v[216:217]
	v_lshl_add_u64 v[80:81], v[80:81], 0, v[218:219]
	v_mul_f32_e32 v76, v76, v82
	v_mul_f32_e32 v72, v72, v76
	v_add_f32_e32 v76, 1.0, v83
	v_mul_f32_e32 v82, 0xbfb8aa3b, v78
	v_rcp_f32_e32 v76, v76
	v_exp_f32_e32 v82, v82
	v_mul_f32_e32 v83, 0xbfb8aa3b, v79
	v_exp_f32_e32 v83, v83
	v_mul_f32_e32 v76, v77, v76
	v_add_f32_e32 v77, 1.0, v82
	v_rcp_f32_e32 v77, v77
	v_add_f32_e32 v82, 1.0, v83
	v_rcp_f32_e32 v82, v82
	v_mul_f32_e32 v73, v73, v76
	v_mul_f32_e32 v76, v78, v77
	v_mul_f32_e32 v77, 0xbfb8aa3b, v68
	v_exp_f32_e32 v77, v77
	v_mul_f32_e32 v74, v74, v76
	v_mul_f32_e32 v76, v79, v82
	v_mul_f32_e32 v75, v75, v76
	v_cvt_pk_bf16_f32 v72, v72, v73
	v_cvt_pk_bf16_f32 v73, v74, v75
	v_add_f32_e32 v74, 1.0, v77
	v_rcp_f32_e32 v74, v74
	v_mul_f32_e32 v75, 0xbfb8aa3b, v69
	v_exp_f32_e32 v75, v75
	global_store_dwordx2 v[80:81], v[72:73], off
	v_mul_f32_e32 v68, v68, v74
	v_mul_f32_e32 v64, v64, v68
	v_add_f32_e32 v68, 1.0, v75
	v_mul_f32_e32 v72, 0xbfb8aa3b, v70
	v_rcp_f32_e32 v68, v68
	v_exp_f32_e32 v72, v72
	v_mul_f32_e32 v73, 0xbfb8aa3b, v71
	v_exp_f32_e32 v73, v73
	v_mul_f32_e32 v68, v69, v68
	v_add_f32_e32 v69, 1.0, v72
	v_rcp_f32_e32 v69, v69
	v_add_f32_e32 v72, 1.0, v73
	v_rcp_f32_e32 v72, v72
	v_mul_f32_e32 v65, v65, v68
	v_mul_f32_e32 v68, v70, v69
	v_mul_f32_e32 v66, v66, v68
	v_mul_f32_e32 v68, v71, v72
	v_cvt_pk_bf16_f32 v64, v64, v65
	v_mul_f32_e32 v67, v67, v68
	v_cvt_pk_bf16_f32 v65, v66, v67
	global_store_dwordx2 v[80:81], v[64:65], off offset:128
	v_mul_f32_e32 v64, 0xbfb8aa3b, v60
	v_exp_f32_e32 v66, v64
	v_mul_f32_e32 v67, 0xbfb8aa3b, v61
	v_exp_f32_e32 v67, v67
	v_add_u32_e32 v64, 0x80, v220
	v_add_f32_e32 v66, 1.0, v66
	v_rcp_f32_e32 v66, v66
	v_mad_i64_i32 v[64:65], vcc, v64, s64, v[216:217]
	v_lshl_add_u64 v[64:65], v[64:65], 0, v[218:219]
	v_mul_f32_e32 v60, v60, v66
	v_mul_f32_e32 v56, v56, v60
	v_add_f32_e32 v60, 1.0, v67
	v_mul_f32_e32 v66, 0xbfb8aa3b, v62
	v_rcp_f32_e32 v60, v60
	v_exp_f32_e32 v66, v66
	v_mul_f32_e32 v67, 0xbfb8aa3b, v63
	v_exp_f32_e32 v67, v67
	v_mul_f32_e32 v60, v61, v60
	v_add_f32_e32 v61, 1.0, v66
	v_rcp_f32_e32 v61, v61
	v_add_f32_e32 v66, 1.0, v67
	v_rcp_f32_e32 v66, v66
	v_mul_f32_e32 v57, v57, v60
	v_mul_f32_e32 v60, v62, v61
	v_mul_f32_e32 v61, 0xbfb8aa3b, v52
	v_exp_f32_e32 v61, v61
	v_mul_f32_e32 v58, v58, v60
	v_mul_f32_e32 v60, v63, v66
	v_mul_f32_e32 v59, v59, v60
	v_cvt_pk_bf16_f32 v56, v56, v57
	v_cvt_pk_bf16_f32 v57, v58, v59
	v_add_f32_e32 v58, 1.0, v61
	v_rcp_f32_e32 v58, v58
	v_mul_f32_e32 v59, 0xbfb8aa3b, v53
	v_exp_f32_e32 v59, v59
	global_store_dwordx2 v[64:65], v[56:57], off
	v_mul_f32_e32 v52, v52, v58
	v_mul_f32_e32 v48, v48, v52
	v_add_f32_e32 v52, 1.0, v59
	v_mul_f32_e32 v56, 0xbfb8aa3b, v54
	v_rcp_f32_e32 v52, v52
	v_exp_f32_e32 v56, v56
	v_mul_f32_e32 v57, 0xbfb8aa3b, v55
	v_exp_f32_e32 v57, v57
	v_mul_f32_e32 v52, v53, v52
	v_add_f32_e32 v53, 1.0, v56
	v_rcp_f32_e32 v53, v53
	v_add_f32_e32 v56, 1.0, v57
	v_rcp_f32_e32 v56, v56
	v_mul_f32_e32 v49, v49, v52
	v_mul_f32_e32 v52, v54, v53
	v_mul_f32_e32 v50, v50, v52
	v_mul_f32_e32 v52, v55, v56
	v_cvt_pk_bf16_f32 v48, v48, v49
	v_mul_f32_e32 v51, v51, v52
	v_cvt_pk_bf16_f32 v49, v50, v51
	global_store_dwordx2 v[64:65], v[48:49], off offset:128
	v_mul_f32_e32 v48, 0xbfb8aa3b, v44
	v_exp_f32_e32 v50, v48
	v_mul_f32_e32 v51, 0xbfb8aa3b, v45
	v_exp_f32_e32 v51, v51
	v_add_u32_e32 v48, 0x90, v220
	v_add_f32_e32 v50, 1.0, v50
	v_rcp_f32_e32 v50, v50
	v_mad_i64_i32 v[48:49], vcc, v48, s64, v[216:217]
	v_lshl_add_u64 v[48:49], v[48:49], 0, v[218:219]
	v_mul_f32_e32 v44, v44, v50
	v_mul_f32_e32 v40, v40, v44
	v_add_f32_e32 v44, 1.0, v51
	v_mul_f32_e32 v50, 0xbfb8aa3b, v46
	v_rcp_f32_e32 v44, v44
	v_exp_f32_e32 v50, v50
	v_mul_f32_e32 v51, 0xbfb8aa3b, v47
	v_exp_f32_e32 v51, v51
	v_mul_f32_e32 v44, v45, v44
	v_add_f32_e32 v45, 1.0, v50
	v_rcp_f32_e32 v45, v45
	v_add_f32_e32 v50, 1.0, v51
	v_rcp_f32_e32 v50, v50
	v_mul_f32_e32 v41, v41, v44
	v_mul_f32_e32 v44, v46, v45
	v_mul_f32_e32 v45, 0xbfb8aa3b, v36
	v_exp_f32_e32 v45, v45
	v_mul_f32_e32 v42, v42, v44
	v_mul_f32_e32 v44, v47, v50
	v_mul_f32_e32 v43, v43, v44
	v_cvt_pk_bf16_f32 v40, v40, v41
	v_cvt_pk_bf16_f32 v41, v42, v43
	v_add_f32_e32 v42, 1.0, v45
	v_rcp_f32_e32 v42, v42
	v_mul_f32_e32 v43, 0xbfb8aa3b, v37
	v_exp_f32_e32 v43, v43
	global_store_dwordx2 v[48:49], v[40:41], off
	v_mul_f32_e32 v36, v36, v42
	v_mul_f32_e32 v32, v32, v36
	v_add_f32_e32 v36, 1.0, v43
	v_mul_f32_e32 v40, 0xbfb8aa3b, v38
	v_rcp_f32_e32 v36, v36
	v_exp_f32_e32 v40, v40
	v_mul_f32_e32 v41, 0xbfb8aa3b, v39
	v_exp_f32_e32 v41, v41
	v_mul_f32_e32 v36, v37, v36
	v_add_f32_e32 v37, 1.0, v40
	v_rcp_f32_e32 v37, v37
	v_add_f32_e32 v40, 1.0, v41
	v_rcp_f32_e32 v40, v40
	v_mul_f32_e32 v33, v33, v36
	v_mul_f32_e32 v36, v38, v37
	v_mul_f32_e32 v34, v34, v36
	v_mul_f32_e32 v36, v39, v40
	v_cvt_pk_bf16_f32 v32, v32, v33
	v_mul_f32_e32 v35, v35, v36
	v_cvt_pk_bf16_f32 v33, v34, v35
	global_store_dwordx2 v[48:49], v[32:33], off offset:128
	v_mul_f32_e32 v32, 0xbfb8aa3b, v28
	v_exp_f32_e32 v34, v32
	v_mul_f32_e32 v35, 0xbfb8aa3b, v29
	v_exp_f32_e32 v35, v35
	v_add_u32_e32 v32, 0xa0, v220
	v_add_f32_e32 v34, 1.0, v34
	v_rcp_f32_e32 v34, v34
	v_mad_i64_i32 v[32:33], vcc, v32, s64, v[216:217]
	v_lshl_add_u64 v[32:33], v[32:33], 0, v[218:219]
	v_mul_f32_e32 v28, v28, v34
	v_mul_f32_e32 v24, v24, v28
	v_add_f32_e32 v28, 1.0, v35
	v_mul_f32_e32 v34, 0xbfb8aa3b, v30
	v_rcp_f32_e32 v28, v28
	v_exp_f32_e32 v34, v34
	v_mul_f32_e32 v35, 0xbfb8aa3b, v31
	v_exp_f32_e32 v35, v35
	v_mul_f32_e32 v28, v29, v28
	v_add_f32_e32 v29, 1.0, v34
	v_rcp_f32_e32 v29, v29
	v_add_f32_e32 v34, 1.0, v35
	v_rcp_f32_e32 v34, v34
	v_mul_f32_e32 v25, v25, v28
	v_mul_f32_e32 v28, v30, v29
	v_mul_f32_e32 v29, 0xbfb8aa3b, v20
	v_exp_f32_e32 v29, v29
	v_mul_f32_e32 v26, v26, v28
	v_mul_f32_e32 v28, v31, v34
	v_mul_f32_e32 v27, v27, v28
	v_cvt_pk_bf16_f32 v24, v24, v25
	v_cvt_pk_bf16_f32 v25, v26, v27
	v_add_f32_e32 v26, 1.0, v29
	v_rcp_f32_e32 v26, v26
	v_mul_f32_e32 v27, 0xbfb8aa3b, v21
	v_exp_f32_e32 v27, v27
	global_store_dwordx2 v[32:33], v[24:25], off
	v_mul_f32_e32 v20, v20, v26
	v_mul_f32_e32 v16, v16, v20
	v_add_f32_e32 v20, 1.0, v27
	v_mul_f32_e32 v24, 0xbfb8aa3b, v22
	v_rcp_f32_e32 v20, v20
	v_exp_f32_e32 v24, v24
	v_mul_f32_e32 v25, 0xbfb8aa3b, v23
	v_exp_f32_e32 v25, v25
	v_mul_f32_e32 v20, v21, v20
	v_add_f32_e32 v21, 1.0, v24
	v_rcp_f32_e32 v21, v21
	v_add_f32_e32 v24, 1.0, v25
	v_rcp_f32_e32 v24, v24
	v_mul_f32_e32 v17, v17, v20
	v_mul_f32_e32 v20, v22, v21
	v_mul_f32_e32 v18, v18, v20
	v_mul_f32_e32 v20, v23, v24
	v_cvt_pk_bf16_f32 v16, v16, v17
	v_mul_f32_e32 v19, v19, v20
	v_cvt_pk_bf16_f32 v17, v18, v19
	global_store_dwordx2 v[32:33], v[16:17], off offset:128
	v_mul_f32_e32 v16, 0xbfb8aa3b, v12
	v_exp_f32_e32 v18, v16
	v_mul_f32_e32 v19, 0xbfb8aa3b, v13
	v_exp_f32_e32 v19, v19
	v_add_u32_e32 v16, 0xb0, v220
	v_add_f32_e32 v18, 1.0, v18
	v_rcp_f32_e32 v18, v18
	v_mad_i64_i32 v[16:17], vcc, v16, s64, v[216:217]
	v_lshl_add_u64 v[16:17], v[16:17], 0, v[218:219]
	v_mul_f32_e32 v12, v12, v18
	v_mul_f32_e32 v8, v8, v12
	v_add_f32_e32 v12, 1.0, v19
	v_mul_f32_e32 v18, 0xbfb8aa3b, v14
	v_rcp_f32_e32 v12, v12
	v_exp_f32_e32 v18, v18
	v_mul_f32_e32 v19, 0xbfb8aa3b, v15
	v_exp_f32_e32 v19, v19
	v_mul_f32_e32 v12, v13, v12
	v_add_f32_e32 v13, 1.0, v18
	v_rcp_f32_e32 v13, v13
	v_add_f32_e32 v18, 1.0, v19
	v_rcp_f32_e32 v18, v18
	v_mul_f32_e32 v9, v9, v12
	v_mul_f32_e32 v12, v14, v13
	v_mul_f32_e32 v13, 0xbfb8aa3b, v4
	v_exp_f32_e32 v13, v13
	v_mul_f32_e32 v10, v10, v12
	v_mul_f32_e32 v12, v15, v18
	v_mul_f32_e32 v11, v11, v12
	v_cvt_pk_bf16_f32 v8, v8, v9
	v_cvt_pk_bf16_f32 v9, v10, v11
	v_add_f32_e32 v10, 1.0, v13
	v_rcp_f32_e32 v10, v10
	v_mul_f32_e32 v11, 0xbfb8aa3b, v5
	v_exp_f32_e32 v11, v11
	global_store_dwordx2 v[16:17], v[8:9], off
	v_mul_f32_e32 v4, v4, v10
	v_mul_f32_e32 v0, v0, v4
	v_add_f32_e32 v4, 1.0, v11
	v_mul_f32_e32 v8, 0xbfb8aa3b, v6
	v_rcp_f32_e32 v4, v4
	v_exp_f32_e32 v8, v8
	v_mul_f32_e32 v9, 0xbfb8aa3b, v7
	v_exp_f32_e32 v9, v9
	v_mul_f32_e32 v4, v5, v4
	v_add_f32_e32 v5, 1.0, v8
	v_rcp_f32_e32 v5, v5
	v_add_f32_e32 v8, 1.0, v9
	v_rcp_f32_e32 v8, v8
	v_mul_f32_e32 v1, v1, v4
	v_mul_f32_e32 v4, v6, v5
	v_mul_f32_e32 v2, v2, v4
	v_mul_f32_e32 v4, v7, v8
	v_mul_f32_e32 v3, v3, v4
	v_cvt_pk_bf16_f32 v0, v0, v1
	v_cvt_pk_bf16_f32 v1, v2, v3
	global_store_dwordx2 v[16:17], v[0:1], off offset:128
	s_waitcnt vmcnt(8)
	s_waitcnt lgkmcnt(0)
	s_barrier
	s_waitcnt lgkmcnt(0)
	v_mfma_f32_16x16x32_bf16 v[124:127], v[140:143], v[184:187], 0
	v_mfma_f32_16x16x32_bf16 v[124:127], v[150:153], v[188:191], v[124:127]
	s_setprio 1
	v_mfma_f32_16x16x32_bf16 v[120:123], v[154:157], v[184:187], 0
	v_mfma_f32_16x16x32_bf16 v[120:123], v[158:161], v[188:191], v[120:123]
	v_mfma_f32_16x16x32_bf16 v[108:111], v[140:143], v[192:195], 0
	v_mfma_f32_16x16x32_bf16 v[108:111], v[150:153], v[196:199], v[108:111]
	v_mfma_f32_16x16x32_bf16 v[104:107], v[154:157], v[192:195], 0
	v_mfma_f32_16x16x32_bf16 v[104:107], v[158:161], v[196:199], v[104:107]
	v_mfma_f32_16x16x32_bf16 v[92:95], v[140:143], v[200:203], 0
	v_mfma_f32_16x16x32_bf16 v[92:95], v[150:153], v[204:207], v[92:95]
	v_mfma_f32_16x16x32_bf16 v[88:91], v[154:157], v[200:203], 0
	v_mfma_f32_16x16x32_bf16 v[88:91], v[158:161], v[204:207], v[88:91]
	v_mfma_f32_16x16x32_bf16 v[76:79], v[140:143], v[208:211], 0
	v_mfma_f32_16x16x32_bf16 v[76:79], v[150:153], v[212:215], v[76:79]
	v_mfma_f32_16x16x32_bf16 v[72:75], v[154:157], v[208:211], 0
	v_mfma_f32_16x16x32_bf16 v[72:75], v[158:161], v[212:215], v[72:75]
	v_mfma_f32_16x16x32_bf16 v[116:119], v[162:165], v[184:187], 0
	v_mfma_f32_16x16x32_bf16 v[116:119], v[166:169], v[188:191], v[116:119]
	v_mfma_f32_16x16x32_bf16 v[112:115], v[170:173], v[184:187], 0
	v_mfma_f32_16x16x32_bf16 v[112:115], v[174:177], v[188:191], v[112:115]
	v_mfma_f32_16x16x32_bf16 v[100:103], v[162:165], v[192:195], 0
	v_mfma_f32_16x16x32_bf16 v[100:103], v[166:169], v[196:199], v[100:103]
	v_mfma_f32_16x16x32_bf16 v[96:99], v[170:173], v[192:195], 0
	v_mfma_f32_16x16x32_bf16 v[96:99], v[174:177], v[196:199], v[96:99]
	v_mfma_f32_16x16x32_bf16 v[84:87], v[162:165], v[200:203], 0
	v_mfma_f32_16x16x32_bf16 v[84:87], v[166:169], v[204:207], v[84:87]
	v_mfma_f32_16x16x32_bf16 v[80:83], v[170:173], v[200:203], 0
	v_mfma_f32_16x16x32_bf16 v[80:83], v[174:177], v[204:207], v[80:83]
	v_mfma_f32_16x16x32_bf16 v[68:71], v[162:165], v[208:211], 0
	v_mfma_f32_16x16x32_bf16 v[68:71], v[166:169], v[212:215], v[68:71]
	s_barrier
	v_mfma_f32_16x16x32_bf16 v[64:67], v[170:173], v[208:211], 0
	v_mfma_f32_16x16x32_bf16 v[64:67], v[174:177], v[212:215], v[64:67]
	s_setprio 0
	s_add_i32 s18, s62, s54
	v_lshl_add_u64 v[178:179], s[46:47], 0, v[130:131]
	s_mov_b32 m0, s18
	ds_read_b128 v[184:187], v149 offset:16384
	ds_read_b128 v[188:191], v149 offset:17408
	ds_read_b128 v[192:195], v149 offset:18432
	ds_read_b128 v[196:199], v149 offset:19456
	ds_read_b128 v[200:203], v149 offset:20480
	ds_read_b128 v[204:207], v149 offset:21504
	ds_read_b128 v[208:211], v149 offset:22528
	ds_read_b128 v[212:215], v149 offset:23552
	global_load_lds_dwordx4 v[178:179], off
	s_add_i32 m0, s18, 0x2000
	s_add_u32 s72, s46, 0x40000
	v_lshl_add_u64 v[216:217], s[46:47], 0, v[128:129]
	s_addc_u32 s73, s47, 0
	s_add_i32 s18, s63, s54
	global_load_lds_dwordx4 v[216:217], off
	v_lshl_add_u64 v[218:219], s[72:73], 0, v[130:131]
	s_mov_b32 m0, s18
	v_lshl_add_u64 v[220:221], s[48:49], 0, v[128:129]
	global_load_lds_dwordx4 v[218:219], off
	v_lshl_add_u64 v[218:219], s[72:73], 0, v[128:129]
	s_add_i32 m0, s18, 0x2000
	s_nop 0
	global_load_lds_dwordx4 v[218:219], off
	v_lshl_add_u64 v[218:219], s[48:49], 0, v[130:131]
	s_mov_b32 m0, s37
	s_nop 0
	global_load_lds_dwordx4 v[218:219], off
	s_mov_b32 m0, s56
	s_nop 0
	global_load_lds_dwordx4 v[220:221], off
	s_waitcnt vmcnt(8)
	s_waitcnt lgkmcnt(0)
	s_barrier
	s_waitcnt lgkmcnt(0)
	v_mfma_f32_16x16x32_bf16 v[60:63], v[140:143], v[184:187], 0
	v_mfma_f32_16x16x32_bf16 v[60:63], v[150:153], v[188:191], v[60:63]
	s_setprio 1
	v_mfma_f32_16x16x32_bf16 v[56:59], v[154:157], v[184:187], 0
	v_mfma_f32_16x16x32_bf16 v[56:59], v[158:161], v[188:191], v[56:59]
	v_mfma_f32_16x16x32_bf16 v[44:47], v[140:143], v[192:195], 0
	v_mfma_f32_16x16x32_bf16 v[44:47], v[150:153], v[196:199], v[44:47]
	v_mfma_f32_16x16x32_bf16 v[40:43], v[154:157], v[192:195], 0
	v_mfma_f32_16x16x32_bf16 v[40:43], v[158:161], v[196:199], v[40:43]
	v_mfma_f32_16x16x32_bf16 v[28:31], v[140:143], v[200:203], 0
	v_mfma_f32_16x16x32_bf16 v[28:31], v[150:153], v[204:207], v[28:31]
	v_mfma_f32_16x16x32_bf16 v[24:27], v[154:157], v[200:203], 0
	v_mfma_f32_16x16x32_bf16 v[24:27], v[158:161], v[204:207], v[24:27]
	v_mfma_f32_16x16x32_bf16 v[12:15], v[140:143], v[208:211], 0
	v_mfma_f32_16x16x32_bf16 v[12:15], v[150:153], v[212:215], v[12:15]
	v_mfma_f32_16x16x32_bf16 v[8:11], v[154:157], v[208:211], 0
	v_mfma_f32_16x16x32_bf16 v[8:11], v[158:161], v[212:215], v[8:11]
	v_mfma_f32_16x16x32_bf16 v[52:55], v[162:165], v[184:187], 0
	v_mfma_f32_16x16x32_bf16 v[52:55], v[166:169], v[188:191], v[52:55]
	v_mfma_f32_16x16x32_bf16 v[48:51], v[170:173], v[184:187], 0
	v_mfma_f32_16x16x32_bf16 v[48:51], v[174:177], v[188:191], v[48:51]
	v_mfma_f32_16x16x32_bf16 v[36:39], v[162:165], v[192:195], 0
	v_mfma_f32_16x16x32_bf16 v[36:39], v[166:169], v[196:199], v[36:39]
	v_mfma_f32_16x16x32_bf16 v[32:35], v[170:173], v[192:195], 0
	v_mfma_f32_16x16x32_bf16 v[32:35], v[174:177], v[196:199], v[32:35]
	v_mfma_f32_16x16x32_bf16 v[20:23], v[162:165], v[200:203], 0
	v_mfma_f32_16x16x32_bf16 v[20:23], v[166:169], v[204:207], v[20:23]
	v_mfma_f32_16x16x32_bf16 v[16:19], v[170:173], v[200:203], 0
	v_mfma_f32_16x16x32_bf16 v[16:19], v[174:177], v[204:207], v[16:19]
	v_mfma_f32_16x16x32_bf16 v[4:7], v[162:165], v[208:211], 0
	v_mfma_f32_16x16x32_bf16 v[4:7], v[166:169], v[212:215], v[4:7]
	s_barrier
	v_mfma_f32_16x16x32_bf16 v[0:3], v[170:173], v[208:211], 0
	v_mfma_f32_16x16x32_bf16 v[0:3], v[174:177], v[212:215], v[0:3]
	s_setprio 0
	s_branch .Lmid_gemm0

.Lmid_gemm0:
	s_add_i32 s18, 0, 0x18000
	s_add_i32 s19, 0, 0x1c000
	v_add_u32_e32 v158, s18, v145
	v_add_u32_e32 v174, s19, v145
	ds_read_b128 v[140:143], v158
	ds_read_b128 v[150:153], v158 offset:1024
	ds_read_b128 v[154:157], v158 offset:2048
	ds_read_b128 v[158:161], v158 offset:3072
	ds_read_b128 v[162:165], v174
	ds_read_b128 v[166:169], v174 offset:1024
	ds_read_b128 v[170:173], v174 offset:2048
	ds_read_b128 v[174:177], v174 offset:3072
	s_add_u32 s48, s48, 0x40000
	s_addc_u32 s49, s49, 0
	s_mov_b32 m0, s57
	v_lshl_add_u64 v[222:223], s[48:49], 0, v[130:131]
	ds_read_b128 v[184:187], v149 offset:32768
	ds_read_b128 v[188:191], v149 offset:33792
	ds_read_b128 v[192:195], v149 offset:34816
	ds_read_b128 v[196:199], v149 offset:35840
	ds_read_b128 v[200:203], v149 offset:36864
	ds_read_b128 v[204:207], v149 offset:37888
	ds_read_b128 v[208:211], v149 offset:38912
	ds_read_b128 v[212:215], v149 offset:39936
	global_load_lds_dwordx4 v[222:223], off
	v_lshl_add_u64 v[222:223], s[48:49], 0, v[128:129]
	s_mov_b32 m0, s58
	s_nop 0
	global_load_lds_dwordx4 v[222:223], off
	s_waitcnt vmcnt(8)
	s_waitcnt lgkmcnt(0)
	s_barrier
	s_waitcnt lgkmcnt(0)
	v_mfma_f32_16x16x32_bf16 v[124:127], v[140:143], v[184:187], v[124:127]
	v_mfma_f32_16x16x32_bf16 v[124:127], v[150:153], v[188:191], v[124:127]
	s_setprio 1
	v_mfma_f32_16x16x32_bf16 v[120:123], v[154:157], v[184:187], v[120:123]
	v_mfma_f32_16x16x32_bf16 v[120:123], v[158:161], v[188:191], v[120:123]
	v_mfma_f32_16x16x32_bf16 v[108:111], v[140:143], v[192:195], v[108:111]
	v_mfma_f32_16x16x32_bf16 v[108:111], v[150:153], v[196:199], v[108:111]
	v_mfma_f32_16x16x32_bf16 v[104:107], v[154:157], v[192:195], v[104:107]
	v_mfma_f32_16x16x32_bf16 v[104:107], v[158:161], v[196:199], v[104:107]
	v_mfma_f32_16x16x32_bf16 v[92:95], v[140:143], v[200:203], v[92:95]
	v_mfma_f32_16x16x32_bf16 v[92:95], v[150:153], v[204:207], v[92:95]
	v_mfma_f32_16x16x32_bf16 v[88:91], v[154:157], v[200:203], v[88:91]
	v_mfma_f32_16x16x32_bf16 v[88:91], v[158:161], v[204:207], v[88:91]
	v_mfma_f32_16x16x32_bf16 v[76:79], v[140:143], v[208:211], v[76:79]
	v_mfma_f32_16x16x32_bf16 v[76:79], v[150:153], v[212:215], v[76:79]
	v_mfma_f32_16x16x32_bf16 v[72:75], v[154:157], v[208:211], v[72:75]
	v_mfma_f32_16x16x32_bf16 v[72:75], v[158:161], v[212:215], v[72:75]
	v_mfma_f32_16x16x32_bf16 v[116:119], v[162:165], v[184:187], v[116:119]
	v_mfma_f32_16x16x32_bf16 v[116:119], v[166:169], v[188:191], v[116:119]
	v_mfma_f32_16x16x32_bf16 v[112:115], v[170:173], v[184:187], v[112:115]
	v_mfma_f32_16x16x32_bf16 v[112:115], v[174:177], v[188:191], v[112:115]
	v_mfma_f32_16x16x32_bf16 v[100:103], v[162:165], v[192:195], v[100:103]
	v_mfma_f32_16x16x32_bf16 v[100:103], v[166:169], v[196:199], v[100:103]
	v_mfma_f32_16x16x32_bf16 v[96:99], v[170:173], v[192:195], v[96:99]
	v_mfma_f32_16x16x32_bf16 v[96:99], v[174:177], v[196:199], v[96:99]
	v_mfma_f32_16x16x32_bf16 v[84:87], v[162:165], v[200:203], v[84:87]
	v_mfma_f32_16x16x32_bf16 v[84:87], v[166:169], v[204:207], v[84:87]
	v_mfma_f32_16x16x32_bf16 v[80:83], v[170:173], v[200:203], v[80:83]
	v_mfma_f32_16x16x32_bf16 v[80:83], v[174:177], v[204:207], v[80:83]
	v_mfma_f32_16x16x32_bf16 v[68:71], v[162:165], v[208:211], v[68:71]
	v_mfma_f32_16x16x32_bf16 v[68:71], v[166:169], v[212:215], v[68:71]
	s_barrier
	v_mfma_f32_16x16x32_bf16 v[64:67], v[170:173], v[208:211], v[64:67]
	v_mfma_f32_16x16x32_bf16 v[64:67], v[174:177], v[212:215], v[64:67]
	s_setprio 0
	s_add_i32 s18, s18, s54
	v_lshl_add_u64 v[178:179], v[178:179], 0, s[6:7]
	s_mov_b32 m0, s18
	ds_read_b128 v[184:187], v149 offset:49152
	ds_read_b128 v[188:191], v149 offset:50176
	ds_read_b128 v[192:195], v149 offset:51200
	ds_read_b128 v[196:199], v149 offset:52224
	ds_read_b128 v[200:203], v149 offset:53248
	ds_read_b128 v[204:207], v149 offset:54272
	ds_read_b128 v[208:211], v149 offset:55296
	ds_read_b128 v[212:215], v149 offset:56320
	global_load_lds_dwordx4 v[178:179], off
	s_add_i32 m0, s18, 0x2000
	s_add_u32 s46, s46, 0x40080
	v_lshl_add_u64 v[178:179], v[216:217], 0, s[6:7]
	s_addc_u32 s47, s47, 0
	s_add_i32 s18, s19, s54
	global_load_lds_dwordx4 v[178:179], off
	v_lshl_add_u64 v[178:179], s[46:47], 0, v[130:131]
	s_mov_b32 m0, s18
	s_nop 0
	global_load_lds_dwordx4 v[178:179], off
	v_lshl_add_u64 v[178:179], s[46:47], 0, v[128:129]
	s_add_i32 m0, s18, 0x2000
	s_nop 0
	global_load_lds_dwordx4 v[178:179], off
	v_lshl_add_u64 v[178:179], v[218:219], 0, s[6:7]
	s_mov_b32 m0, s60
	s_nop 0
	global_load_lds_dwordx4 v[178:179], off
	v_lshl_add_u64 v[178:179], v[220:221], 0, s[6:7]
	s_mov_b32 m0, s61
	s_nop 0
	global_load_lds_dwordx4 v[178:179], off
	s_waitcnt vmcnt(8)
	s_waitcnt lgkmcnt(0)
	s_barrier
	s_waitcnt lgkmcnt(0)
	v_mfma_f32_16x16x32_bf16 v[60:63], v[140:143], v[184:187], v[60:63]
	v_mfma_f32_16x16x32_bf16 v[60:63], v[150:153], v[188:191], v[60:63]
	s_setprio 1
	v_mfma_f32_16x16x32_bf16 v[56:59], v[154:157], v[184:187], v[56:59]
	v_mfma_f32_16x16x32_bf16 v[56:59], v[158:161], v[188:191], v[56:59]
	v_mfma_f32_16x16x32_bf16 v[44:47], v[140:143], v[192:195], v[44:47]
	v_mfma_f32_16x16x32_bf16 v[44:47], v[150:153], v[196:199], v[44:47]
	v_mfma_f32_16x16x32_bf16 v[40:43], v[154:157], v[192:195], v[40:43]
	v_mfma_f32_16x16x32_bf16 v[40:43], v[158:161], v[196:199], v[40:43]
	v_mfma_f32_16x16x32_bf16 v[28:31], v[140:143], v[200:203], v[28:31]
	v_mfma_f32_16x16x32_bf16 v[28:31], v[150:153], v[204:207], v[28:31]
	v_mfma_f32_16x16x32_bf16 v[24:27], v[154:157], v[200:203], v[24:27]
	v_mfma_f32_16x16x32_bf16 v[24:27], v[158:161], v[204:207], v[24:27]
	v_mfma_f32_16x16x32_bf16 v[12:15], v[140:143], v[208:211], v[12:15]
	v_mfma_f32_16x16x32_bf16 v[12:15], v[150:153], v[212:215], v[12:15]
	v_mfma_f32_16x16x32_bf16 v[8:11], v[154:157], v[208:211], v[8:11]
	v_mfma_f32_16x16x32_bf16 v[8:11], v[158:161], v[212:215], v[8:11]
	v_mfma_f32_16x16x32_bf16 v[52:55], v[162:165], v[184:187], v[52:55]
	v_mfma_f32_16x16x32_bf16 v[52:55], v[166:169], v[188:191], v[52:55]
	v_mfma_f32_16x16x32_bf16 v[48:51], v[170:173], v[184:187], v[48:51]
	v_mfma_f32_16x16x32_bf16 v[48:51], v[174:177], v[188:191], v[48:51]
	v_mfma_f32_16x16x32_bf16 v[36:39], v[162:165], v[192:195], v[36:39]
	v_mfma_f32_16x16x32_bf16 v[36:39], v[166:169], v[196:199], v[36:39]
	v_mfma_f32_16x16x32_bf16 v[32:35], v[170:173], v[192:195], v[32:35]
	v_mfma_f32_16x16x32_bf16 v[32:35], v[174:177], v[196:199], v[32:35]
	v_mfma_f32_16x16x32_bf16 v[20:23], v[162:165], v[200:203], v[20:23]
	v_mfma_f32_16x16x32_bf16 v[20:23], v[166:169], v[204:207], v[20:23]
	v_mfma_f32_16x16x32_bf16 v[16:19], v[170:173], v[200:203], v[16:19]
	v_mfma_f32_16x16x32_bf16 v[16:19], v[174:177], v[204:207], v[16:19]
	v_mfma_f32_16x16x32_bf16 v[4:7], v[162:165], v[208:211], v[4:7]
	v_mfma_f32_16x16x32_bf16 v[4:7], v[166:169], v[212:215], v[4:7]
	s_barrier
	v_mfma_f32_16x16x32_bf16 v[0:3], v[170:173], v[208:211], v[0:3]
	v_mfma_f32_16x16x32_bf16 v[0:3], v[174:177], v[212:215], v[0:3]
	s_setprio 0
	s_add_i32 s70, s70, 2
	s_add_u32 s44, s44, 0x100
	s_addc_u32 s45, s45, 0
	s_add_u32 s68, s68, 0x100
	s_addc_u32 s69, s69, 0
	s_cmp_gt_u32 s70, 13
	s_cbranch_scc0 .LBB0_184
	s_and_b64 vcc, s[8:9], s[4:5]
	s_and_b64 vcc, vcc, exec
	s_cbranch_vccnz .Lpre_0
	s_and_b64 vcc, exec, s[8:9]
	s_cbranch_vccz .LBB0_187
	s_barrier

.Lpre_4:
	s_mov_b32 s98, s69
	s_mov_b32 s100, s46
	s_mov_b32 s69, s18
	s_mov_b32 s46, s30
	s_mov_b64 s[52:53], s[44:45]
	s_mov_b64 s[48:49], s[36:37]
	s_add_i32 s63, s63, 1
	s_mul_i32 s10, s63, s21
	s_mul_hi_u32 s11, s63, s20
	s_add_i32 s11, s11, s10
	s_mul_i32 s10, s63, s20
	s_add_u32 s36, s10, s2
	s_addc_u32 s37, s11, s3
	v_cmp_gt_i64_e32 vcc, s[36:37], v[138:139]
	v_cmp_lt_i64_e64 s[10:11], s[36:37], v[136:137]
	s_cbranch_vccnz .LBB0_723_pk4
	s_lshr_b32 s18, s36, 3
	s_and_b32 s30, s36, 7
	s_lshl_b32 s30, s30, 1
	s_cmp_ge_u32 s18, 0xb0
	s_cbranch_scc0 .Ldec_4_pk4
	s_sub_u32 s18, s18, 0xb0
	s_add_u32 s30, s30, 1

.LBB0_723_pk4:
	s_ashr_i32 s31, s30, 31
	s_lshl_b64 s[36:37], s[30:31], 19
	s_add_u32 s36, s80, s36
	s_addc_u32 s37, s81, s37
	s_and_b64 s[44:45], s[10:11], exec
	s_cselect_b32 s31, s37, s49
	s_cselect_b32 s70, s36, s48
	s_ashr_i32 s19, s18, 31
	s_lshl_b64 s[44:45], s[18:19], 19
	s_add_u32 s44, s56, s44
	s_addc_u32 s45, s57, s45
	s_and_b64 s[54:55], s[10:11], exec
	s_cselect_b32 s19, s45, s53
	s_cselect_b32 s71, s44, s52
	s_add_u32 s48, s48, 0x40080
	s_addc_u32 s49, s49, 0
	s_add_u32 s72, s52, 0x100
	s_addc_u32 s73, s53, 0
	s_mov_b32 s74, -2
	ds_read_b128 v[140:143], v147
	ds_read_b128 v[150:153], v147 offset:1024
	ds_read_b128 v[154:157], v147 offset:2048
	ds_read_b128 v[158:161], v147 offset:3072
	ds_read_b128 v[162:165], v148
	ds_read_b128 v[166:169], v148 offset:1024
	ds_read_b128 v[170:173], v148 offset:2048
	ds_read_b128 v[174:177], v148 offset:3072
	s_add_u32 s52, s48, 0xfffc0080
	s_addc_u32 s53, s49, -1
	s_cmp_eq_u32 s74, 12
	s_cselect_b32 s55, s31, s53
	s_cselect_b32 s54, s70, s52
	s_cselect_b32 s53, s19, s73
	s_cselect_b32 s52, s71, s72
	v_lshl_add_u64 v[178:179], s[48:49], 0, v[132:133]
	s_add_i32 m0, s47, 0xc000
	ds_read_b128 v[184:187], v149
	ds_read_b128 v[188:191], v149 offset:1024
	ds_read_b128 v[192:195], v149 offset:2048
	ds_read_b128 v[196:199], v149 offset:3072
	ds_read_b128 v[200:203], v149 offset:4096
	ds_read_b128 v[204:207], v149 offset:5120
	ds_read_b128 v[208:211], v149 offset:6144
	ds_read_b128 v[212:215], v149 offset:7168
	global_load_lds_dwordx4 v[178:179], off
	v_lshl_add_u64 v[178:179], s[48:49], 0, v[134:135]
	s_add_i32 m0, s47, 0xe000
	s_nop 0
	global_load_lds_dwordx4 v[178:179], off
	s_barrier
	v_mul_f32_e32 v221, 0xbfb8aa3b, v124
	v_exp_f32_e32 v221, v221
	v_mul_f32_e32 v224, 0xbfb8aa3b, v125
	v_exp_f32_e32 v224, v224
	v_lshl_or_b32 v218, s98, 7, v146
	v_add_f32_e32 v221, 1.0, v221
	v_rcp_f32_e32 v221, v221
	v_lshl_add_u32 v220, s100, 8, v144
	v_ashrrev_i32_e32 v219, 31, v218
	v_mov_b64_e32 v[216:217], s[22:23]
	v_mul_f32_e32 v124, v124, v221
	v_mul_f32_e32 v120, v120, v124
	v_add_f32_e32 v124, 1.0, v224
	v_mul_f32_e32 v221, 0xbfb8aa3b, v126
	v_rcp_f32_e32 v124, v124
	v_exp_f32_e32 v221, v221
	v_mul_f32_e32 v224, 0xbfb8aa3b, v127
	v_exp_f32_e32 v224, v224
	v_mul_f32_e32 v124, v125, v124
	v_add_f32_e32 v125, 1.0, v221
	v_rcp_f32_e32 v125, v125
	v_add_f32_e32 v221, 1.0, v224
	v_rcp_f32_e32 v221, v221
	v_mul_f32_e32 v121, v121, v124
	v_mul_f32_e32 v124, v126, v125
	v_mul_f32_e32 v125, 0xbfb8aa3b, v116
	v_exp_f32_e32 v125, v125
	v_mul_f32_e32 v122, v122, v124
	v_mul_f32_e32 v124, v127, v221
	v_mul_f32_e32 v123, v123, v124
	v_cvt_pk_bf16_f32 v120, v120, v121
	v_cvt_pk_bf16_f32 v121, v122, v123
	v_add_f32_e32 v122, 1.0, v125
	v_rcp_f32_e32 v122, v122
	v_mul_f32_e32 v123, 0xbfb8aa3b, v117
	v_exp_f32_e32 v123, v123
	v_mad_i64_i32 v[222:223], vcc, v220, s68, v[216:217]
	v_lshlrev_b64 v[218:219], 1, v[218:219]
	v_lshl_add_u64 v[222:223], v[222:223], 0, v[218:219]
	v_mul_f32_e32 v116, v116, v122
	global_store_dwordx2 v[222:223], v[120:121], off
	v_mul_f32_e32 v112, v112, v116
	v_add_f32_e32 v116, 1.0, v123
	v_mul_f32_e32 v120, 0xbfb8aa3b, v118
	v_rcp_f32_e32 v116, v116
	v_exp_f32_e32 v120, v120
	v_mul_f32_e32 v121, 0xbfb8aa3b, v119
	v_exp_f32_e32 v121, v121
	v_mul_f32_e32 v116, v117, v116
	v_add_f32_e32 v117, 1.0, v120
	v_rcp_f32_e32 v117, v117
	v_add_f32_e32 v120, 1.0, v121
	v_rcp_f32_e32 v120, v120
	v_mul_f32_e32 v113, v113, v116
	v_mul_f32_e32 v116, v118, v117
	v_mul_f32_e32 v114, v114, v116
	v_mul_f32_e32 v116, v119, v120
	v_cvt_pk_bf16_f32 v112, v112, v113
	v_mul_f32_e32 v115, v115, v116
	v_cvt_pk_bf16_f32 v113, v114, v115
	global_store_dwordx2 v[222:223], v[112:113], off offset:128
	v_mul_f32_e32 v112, 0xbfb8aa3b, v108
	v_exp_f32_e32 v114, v112
	v_mul_f32_e32 v115, 0xbfb8aa3b, v109
	v_exp_f32_e32 v115, v115
	v_or_b32_e32 v112, 16, v220
	v_add_f32_e32 v114, 1.0, v114
	v_rcp_f32_e32 v114, v114
	v_mad_i64_i32 v[112:113], vcc, v112, s68, v[216:217]
	v_lshl_add_u64 v[112:113], v[112:113], 0, v[218:219]
	v_mul_f32_e32 v108, v108, v114
	v_mul_f32_e32 v104, v104, v108
	v_add_f32_e32 v108, 1.0, v115
	v_mul_f32_e32 v114, 0xbfb8aa3b, v110
	v_rcp_f32_e32 v108, v108
	v_exp_f32_e32 v114, v114
	v_mul_f32_e32 v115, 0xbfb8aa3b, v111
	v_exp_f32_e32 v115, v115
	v_mul_f32_e32 v108, v109, v108
	v_add_f32_e32 v109, 1.0, v114
	v_rcp_f32_e32 v109, v109
	v_add_f32_e32 v114, 1.0, v115
	v_rcp_f32_e32 v114, v114
	v_mul_f32_e32 v105, v105, v108
	v_mul_f32_e32 v108, v110, v109
	v_mul_f32_e32 v109, 0xbfb8aa3b, v100
	v_exp_f32_e32 v109, v109
	v_mul_f32_e32 v106, v106, v108
	v_mul_f32_e32 v108, v111, v114
	v_mul_f32_e32 v107, v107, v108
	v_cvt_pk_bf16_f32 v104, v104, v105
	v_cvt_pk_bf16_f32 v105, v106, v107
	v_add_f32_e32 v106, 1.0, v109
	v_rcp_f32_e32 v106, v106
	v_mul_f32_e32 v107, 0xbfb8aa3b, v101
	v_exp_f32_e32 v107, v107
	global_store_dwordx2 v[112:113], v[104:105], off
	v_mul_f32_e32 v100, v100, v106
	v_mul_f32_e32 v96, v96, v100
	v_add_f32_e32 v100, 1.0, v107
	v_mul_f32_e32 v104, 0xbfb8aa3b, v102
	v_rcp_f32_e32 v100, v100
	v_exp_f32_e32 v104, v104
	v_mul_f32_e32 v105, 0xbfb8aa3b, v103
	v_exp_f32_e32 v105, v105
	v_mul_f32_e32 v100, v101, v100
	v_add_f32_e32 v101, 1.0, v104
	v_rcp_f32_e32 v101, v101
	v_add_f32_e32 v104, 1.0, v105
	v_rcp_f32_e32 v104, v104
	v_mul_f32_e32 v97, v97, v100
	v_mul_f32_e32 v100, v102, v101
	v_mul_f32_e32 v98, v98, v100
	v_mul_f32_e32 v100, v103, v104
	v_cvt_pk_bf16_f32 v96, v96, v97
	v_mul_f32_e32 v99, v99, v100
	v_cvt_pk_bf16_f32 v97, v98, v99
	global_store_dwordx2 v[112:113], v[96:97], off offset:128
	v_mul_f32_e32 v96, 0xbfb8aa3b, v92
	v_exp_f32_e32 v98, v96
	v_mul_f32_e32 v99, 0xbfb8aa3b, v93
	v_exp_f32_e32 v99, v99
	v_or_b32_e32 v96, 32, v220
	v_add_f32_e32 v98, 1.0, v98
	v_rcp_f32_e32 v98, v98
	v_mad_i64_i32 v[96:97], vcc, v96, s68, v[216:217]
	v_lshl_add_u64 v[96:97], v[96:97], 0, v[218:219]
	v_mul_f32_e32 v92, v92, v98
	v_mul_f32_e32 v88, v88, v92
	v_add_f32_e32 v92, 1.0, v99
	v_mul_f32_e32 v98, 0xbfb8aa3b, v94
	v_rcp_f32_e32 v92, v92
	v_exp_f32_e32 v98, v98
	v_mul_f32_e32 v99, 0xbfb8aa3b, v95
	v_exp_f32_e32 v99, v99
	v_mul_f32_e32 v92, v93, v92
	v_add_f32_e32 v93, 1.0, v98
	v_rcp_f32_e32 v93, v93
	v_add_f32_e32 v98, 1.0, v99
	v_rcp_f32_e32 v98, v98
	v_mul_f32_e32 v89, v89, v92
	v_mul_f32_e32 v92, v94, v93
	v_mul_f32_e32 v93, 0xbfb8aa3b, v84
	v_exp_f32_e32 v93, v93
	v_mul_f32_e32 v90, v90, v92
	v_mul_f32_e32 v92, v95, v98
	v_mul_f32_e32 v91, v91, v92
	v_cvt_pk_bf16_f32 v88, v88, v89
	v_cvt_pk_bf16_f32 v89, v90, v91
	v_add_f32_e32 v90, 1.0, v93
	v_rcp_f32_e32 v90, v90
	v_mul_f32_e32 v91, 0xbfb8aa3b, v85
	v_exp_f32_e32 v91, v91
	global_store_dwordx2 v[96:97], v[88:89], off
	v_mul_f32_e32 v84, v84, v90
	v_mul_f32_e32 v80, v80, v84
	v_add_f32_e32 v84, 1.0, v91
	v_mul_f32_e32 v88, 0xbfb8aa3b, v86
	v_rcp_f32_e32 v84, v84
	v_exp_f32_e32 v88, v88
	v_mul_f32_e32 v89, 0xbfb8aa3b, v87
	v_exp_f32_e32 v89, v89
	v_mul_f32_e32 v84, v85, v84
	v_add_f32_e32 v85, 1.0, v88
	v_rcp_f32_e32 v85, v85
	v_add_f32_e32 v88, 1.0, v89
	v_rcp_f32_e32 v88, v88
	v_mul_f32_e32 v81, v81, v84
	v_mul_f32_e32 v84, v86, v85
	v_mul_f32_e32 v82, v82, v84
	v_mul_f32_e32 v84, v87, v88
	v_cvt_pk_bf16_f32 v80, v80, v81
	v_mul_f32_e32 v83, v83, v84
	v_cvt_pk_bf16_f32 v81, v82, v83
	global_store_dwordx2 v[96:97], v[80:81], off offset:128
	v_mul_f32_e32 v80, 0xbfb8aa3b, v76
	v_exp_f32_e32 v82, v80
	v_mul_f32_e32 v83, 0xbfb8aa3b, v77
	v_exp_f32_e32 v83, v83
	v_or_b32_e32 v80, 48, v220
	v_add_f32_e32 v82, 1.0, v82
	v_rcp_f32_e32 v82, v82
	v_mad_i64_i32 v[80:81], vcc, v80, s68, v[216:217]
	v_lshl_add_u64 v[80:81], v[80:81], 0, v[218:219]
	v_mul_f32_e32 v76, v76, v82
	v_mul_f32_e32 v72, v72, v76
	v_add_f32_e32 v76, 1.0, v83
	v_mul_f32_e32 v82, 0xbfb8aa3b, v78
	v_rcp_f32_e32 v76, v76
	v_exp_f32_e32 v82, v82
	v_mul_f32_e32 v83, 0xbfb8aa3b, v79
	v_exp_f32_e32 v83, v83
	v_mul_f32_e32 v76, v77, v76
	v_add_f32_e32 v77, 1.0, v82
	v_rcp_f32_e32 v77, v77
	v_add_f32_e32 v82, 1.0, v83
	v_rcp_f32_e32 v82, v82
	v_mul_f32_e32 v73, v73, v76
	v_mul_f32_e32 v76, v78, v77
	v_mul_f32_e32 v77, 0xbfb8aa3b, v68
	v_exp_f32_e32 v77, v77
	v_mul_f32_e32 v74, v74, v76
	v_mul_f32_e32 v76, v79, v82
	v_mul_f32_e32 v75, v75, v76
	v_cvt_pk_bf16_f32 v72, v72, v73
	v_cvt_pk_bf16_f32 v73, v74, v75
	v_add_f32_e32 v74, 1.0, v77
	v_rcp_f32_e32 v74, v74
	v_mul_f32_e32 v75, 0xbfb8aa3b, v69
	v_exp_f32_e32 v75, v75
	global_store_dwordx2 v[80:81], v[72:73], off
	v_mul_f32_e32 v68, v68, v74
	v_mul_f32_e32 v64, v64, v68
	v_add_f32_e32 v68, 1.0, v75
	v_mul_f32_e32 v72, 0xbfb8aa3b, v70
	v_rcp_f32_e32 v68, v68
	v_exp_f32_e32 v72, v72
	v_mul_f32_e32 v73, 0xbfb8aa3b, v71
	v_exp_f32_e32 v73, v73
	v_mul_f32_e32 v68, v69, v68
	v_add_f32_e32 v69, 1.0, v72
	v_rcp_f32_e32 v69, v69
	v_add_f32_e32 v72, 1.0, v73
	v_rcp_f32_e32 v72, v72
	v_mul_f32_e32 v65, v65, v68
	v_mul_f32_e32 v68, v70, v69
	v_mul_f32_e32 v66, v66, v68
	v_mul_f32_e32 v68, v71, v72
	v_cvt_pk_bf16_f32 v64, v64, v65
	v_mul_f32_e32 v67, v67, v68
	v_cvt_pk_bf16_f32 v65, v66, v67
	global_store_dwordx2 v[80:81], v[64:65], off offset:128
	v_mul_f32_e32 v64, 0xbfb8aa3b, v60
	v_exp_f32_e32 v66, v64
	v_mul_f32_e32 v67, 0xbfb8aa3b, v61
	v_exp_f32_e32 v67, v67
	v_add_u32_e32 v64, 0x80, v220
	v_add_f32_e32 v66, 1.0, v66
	v_rcp_f32_e32 v66, v66
	v_mad_i64_i32 v[64:65], vcc, v64, s68, v[216:217]
	v_lshl_add_u64 v[64:65], v[64:65], 0, v[218:219]
	v_mul_f32_e32 v60, v60, v66
	v_mul_f32_e32 v56, v56, v60
	v_add_f32_e32 v60, 1.0, v67
	v_mul_f32_e32 v66, 0xbfb8aa3b, v62
	v_rcp_f32_e32 v60, v60
	v_exp_f32_e32 v66, v66
	v_mul_f32_e32 v67, 0xbfb8aa3b, v63
	v_exp_f32_e32 v67, v67
	v_mul_f32_e32 v60, v61, v60
	v_add_f32_e32 v61, 1.0, v66
	v_rcp_f32_e32 v61, v61
	v_add_f32_e32 v66, 1.0, v67
	v_rcp_f32_e32 v66, v66
	v_mul_f32_e32 v57, v57, v60
	v_mul_f32_e32 v60, v62, v61
	v_mul_f32_e32 v61, 0xbfb8aa3b, v52
	v_exp_f32_e32 v61, v61
	v_mul_f32_e32 v58, v58, v60
	v_mul_f32_e32 v60, v63, v66
	v_mul_f32_e32 v59, v59, v60
	v_cvt_pk_bf16_f32 v56, v56, v57
	v_cvt_pk_bf16_f32 v57, v58, v59
	v_add_f32_e32 v58, 1.0, v61
	v_rcp_f32_e32 v58, v58
	v_mul_f32_e32 v59, 0xbfb8aa3b, v53
	v_exp_f32_e32 v59, v59
	global_store_dwordx2 v[64:65], v[56:57], off
	v_mul_f32_e32 v52, v52, v58
	v_mul_f32_e32 v48, v48, v52
	v_add_f32_e32 v52, 1.0, v59
	v_mul_f32_e32 v56, 0xbfb8aa3b, v54
	v_rcp_f32_e32 v52, v52
	v_exp_f32_e32 v56, v56
	v_mul_f32_e32 v57, 0xbfb8aa3b, v55
	v_exp_f32_e32 v57, v57
	v_mul_f32_e32 v52, v53, v52
	v_add_f32_e32 v53, 1.0, v56
	v_rcp_f32_e32 v53, v53
	v_add_f32_e32 v56, 1.0, v57
	v_rcp_f32_e32 v56, v56
	v_mul_f32_e32 v49, v49, v52
	v_mul_f32_e32 v52, v54, v53
	v_mul_f32_e32 v50, v50, v52
	v_mul_f32_e32 v52, v55, v56
	v_cvt_pk_bf16_f32 v48, v48, v49
	v_mul_f32_e32 v51, v51, v52
	v_cvt_pk_bf16_f32 v49, v50, v51
	global_store_dwordx2 v[64:65], v[48:49], off offset:128
	v_mul_f32_e32 v48, 0xbfb8aa3b, v44
	v_exp_f32_e32 v50, v48
	v_mul_f32_e32 v51, 0xbfb8aa3b, v45
	v_exp_f32_e32 v51, v51
	v_add_u32_e32 v48, 0x90, v220
	v_add_f32_e32 v50, 1.0, v50
	v_rcp_f32_e32 v50, v50
	v_mad_i64_i32 v[48:49], vcc, v48, s68, v[216:217]
	v_lshl_add_u64 v[48:49], v[48:49], 0, v[218:219]
	v_mul_f32_e32 v44, v44, v50
	v_mul_f32_e32 v40, v40, v44
	v_add_f32_e32 v44, 1.0, v51
	v_mul_f32_e32 v50, 0xbfb8aa3b, v46
	v_rcp_f32_e32 v44, v44
	v_exp_f32_e32 v50, v50
	v_mul_f32_e32 v51, 0xbfb8aa3b, v47
	v_exp_f32_e32 v51, v51
	v_mul_f32_e32 v44, v45, v44
	v_add_f32_e32 v45, 1.0, v50
	v_rcp_f32_e32 v45, v45
	v_add_f32_e32 v50, 1.0, v51
	v_rcp_f32_e32 v50, v50
	v_mul_f32_e32 v41, v41, v44
	v_mul_f32_e32 v44, v46, v45
	v_mul_f32_e32 v45, 0xbfb8aa3b, v36
	v_exp_f32_e32 v45, v45
	v_mul_f32_e32 v42, v42, v44
	v_mul_f32_e32 v44, v47, v50
	v_mul_f32_e32 v43, v43, v44
	v_cvt_pk_bf16_f32 v40, v40, v41
	v_cvt_pk_bf16_f32 v41, v42, v43
	v_add_f32_e32 v42, 1.0, v45
	v_rcp_f32_e32 v42, v42
	v_mul_f32_e32 v43, 0xbfb8aa3b, v37
	v_exp_f32_e32 v43, v43
	global_store_dwordx2 v[48:49], v[40:41], off
	v_mul_f32_e32 v36, v36, v42
	v_mul_f32_e32 v32, v32, v36
	v_add_f32_e32 v36, 1.0, v43
	v_mul_f32_e32 v40, 0xbfb8aa3b, v38
	v_rcp_f32_e32 v36, v36
	v_exp_f32_e32 v40, v40
	v_mul_f32_e32 v41, 0xbfb8aa3b, v39
	v_exp_f32_e32 v41, v41
	v_mul_f32_e32 v36, v37, v36
	v_add_f32_e32 v37, 1.0, v40
	v_rcp_f32_e32 v37, v37
	v_add_f32_e32 v40, 1.0, v41
	v_rcp_f32_e32 v40, v40
	v_mul_f32_e32 v33, v33, v36
	v_mul_f32_e32 v36, v38, v37
	v_mul_f32_e32 v34, v34, v36
	v_mul_f32_e32 v36, v39, v40
	v_cvt_pk_bf16_f32 v32, v32, v33
	v_mul_f32_e32 v35, v35, v36
	v_cvt_pk_bf16_f32 v33, v34, v35
	global_store_dwordx2 v[48:49], v[32:33], off offset:128
	v_mul_f32_e32 v32, 0xbfb8aa3b, v28
	v_exp_f32_e32 v34, v32
	v_mul_f32_e32 v35, 0xbfb8aa3b, v29
	v_exp_f32_e32 v35, v35
	v_add_u32_e32 v32, 0xa0, v220
	v_add_f32_e32 v34, 1.0, v34
	v_rcp_f32_e32 v34, v34
	v_mad_i64_i32 v[32:33], vcc, v32, s68, v[216:217]
	v_lshl_add_u64 v[32:33], v[32:33], 0, v[218:219]
	v_mul_f32_e32 v28, v28, v34
	v_mul_f32_e32 v24, v24, v28
	v_add_f32_e32 v28, 1.0, v35
	v_mul_f32_e32 v34, 0xbfb8aa3b, v30
	v_rcp_f32_e32 v28, v28
	v_exp_f32_e32 v34, v34
	v_mul_f32_e32 v35, 0xbfb8aa3b, v31
	v_exp_f32_e32 v35, v35
	v_mul_f32_e32 v28, v29, v28
	v_add_f32_e32 v29, 1.0, v34
	v_rcp_f32_e32 v29, v29
	v_add_f32_e32 v34, 1.0, v35
	v_rcp_f32_e32 v34, v34
	v_mul_f32_e32 v25, v25, v28
	v_mul_f32_e32 v28, v30, v29
	v_mul_f32_e32 v29, 0xbfb8aa3b, v20
	v_exp_f32_e32 v29, v29
	v_mul_f32_e32 v26, v26, v28
	v_mul_f32_e32 v28, v31, v34
	v_mul_f32_e32 v27, v27, v28
	v_cvt_pk_bf16_f32 v24, v24, v25
	v_cvt_pk_bf16_f32 v25, v26, v27
	v_add_f32_e32 v26, 1.0, v29
	v_rcp_f32_e32 v26, v26
	v_mul_f32_e32 v27, 0xbfb8aa3b, v21
	v_exp_f32_e32 v27, v27
	global_store_dwordx2 v[32:33], v[24:25], off
	v_mul_f32_e32 v20, v20, v26
	v_mul_f32_e32 v16, v16, v20
	v_add_f32_e32 v20, 1.0, v27
	v_mul_f32_e32 v24, 0xbfb8aa3b, v22
	v_rcp_f32_e32 v20, v20
	v_exp_f32_e32 v24, v24
	v_mul_f32_e32 v25, 0xbfb8aa3b, v23
	v_exp_f32_e32 v25, v25
	v_mul_f32_e32 v20, v21, v20
	v_add_f32_e32 v21, 1.0, v24
	v_rcp_f32_e32 v21, v21
	v_add_f32_e32 v24, 1.0, v25
	v_rcp_f32_e32 v24, v24
	v_mul_f32_e32 v17, v17, v20
	v_mul_f32_e32 v20, v22, v21
	v_mul_f32_e32 v18, v18, v20
	v_mul_f32_e32 v20, v23, v24
	v_cvt_pk_bf16_f32 v16, v16, v17
	v_mul_f32_e32 v19, v19, v20
	v_cvt_pk_bf16_f32 v17, v18, v19
	global_store_dwordx2 v[32:33], v[16:17], off offset:128
	v_mul_f32_e32 v16, 0xbfb8aa3b, v12
	v_exp_f32_e32 v18, v16
	v_mul_f32_e32 v19, 0xbfb8aa3b, v13
	v_exp_f32_e32 v19, v19
	v_add_u32_e32 v16, 0xb0, v220
	v_add_f32_e32 v18, 1.0, v18
	v_rcp_f32_e32 v18, v18
	v_mad_i64_i32 v[16:17], vcc, v16, s68, v[216:217]
	v_lshl_add_u64 v[16:17], v[16:17], 0, v[218:219]
	v_mul_f32_e32 v12, v12, v18
	v_mul_f32_e32 v8, v8, v12
	v_add_f32_e32 v12, 1.0, v19
	v_mul_f32_e32 v18, 0xbfb8aa3b, v14
	v_rcp_f32_e32 v12, v12
	v_exp_f32_e32 v18, v18
	v_mul_f32_e32 v19, 0xbfb8aa3b, v15
	v_exp_f32_e32 v19, v19
	v_mul_f32_e32 v12, v13, v12
	v_add_f32_e32 v13, 1.0, v18
	v_rcp_f32_e32 v13, v13
	v_add_f32_e32 v18, 1.0, v19
	v_rcp_f32_e32 v18, v18
	v_mul_f32_e32 v9, v9, v12
	v_mul_f32_e32 v12, v14, v13
	v_mul_f32_e32 v13, 0xbfb8aa3b, v4
	v_exp_f32_e32 v13, v13
	v_mul_f32_e32 v10, v10, v12
	v_mul_f32_e32 v12, v15, v18
	v_mul_f32_e32 v11, v11, v12
	v_cvt_pk_bf16_f32 v8, v8, v9
	v_cvt_pk_bf16_f32 v9, v10, v11
	v_add_f32_e32 v10, 1.0, v13
	v_rcp_f32_e32 v10, v10
	v_mul_f32_e32 v11, 0xbfb8aa3b, v5
	v_exp_f32_e32 v11, v11
	global_store_dwordx2 v[16:17], v[8:9], off
	v_mul_f32_e32 v4, v4, v10
	v_mul_f32_e32 v0, v0, v4
	v_add_f32_e32 v4, 1.0, v11
	v_mul_f32_e32 v8, 0xbfb8aa3b, v6
	v_rcp_f32_e32 v4, v4
	v_exp_f32_e32 v8, v8
	v_mul_f32_e32 v9, 0xbfb8aa3b, v7
	v_exp_f32_e32 v9, v9
	v_mul_f32_e32 v4, v5, v4
	v_add_f32_e32 v5, 1.0, v8
	v_rcp_f32_e32 v5, v5
	v_add_f32_e32 v8, 1.0, v9
	v_rcp_f32_e32 v8, v8
	v_mul_f32_e32 v1, v1, v4
	v_mul_f32_e32 v4, v6, v5
	v_mul_f32_e32 v2, v2, v4
	v_mul_f32_e32 v4, v7, v8
	v_mul_f32_e32 v3, v3, v4
	v_cvt_pk_bf16_f32 v0, v0, v1
	v_cvt_pk_bf16_f32 v1, v2, v3
	global_store_dwordx2 v[16:17], v[0:1], off offset:128
	s_waitcnt vmcnt(8)
	s_waitcnt lgkmcnt(0)
	s_barrier
	s_waitcnt lgkmcnt(0)
	v_mfma_f32_16x16x32_bf16 v[124:127], v[140:143], v[184:187], 0
	v_mfma_f32_16x16x32_bf16 v[124:127], v[150:153], v[188:191], v[124:127]
	s_setprio 1
	v_mfma_f32_16x16x32_bf16 v[120:123], v[154:157], v[184:187], 0
	v_mfma_f32_16x16x32_bf16 v[120:123], v[158:161], v[188:191], v[120:123]
	v_mfma_f32_16x16x32_bf16 v[108:111], v[140:143], v[192:195], 0
	v_mfma_f32_16x16x32_bf16 v[108:111], v[150:153], v[196:199], v[108:111]
	v_mfma_f32_16x16x32_bf16 v[104:107], v[154:157], v[192:195], 0
	v_mfma_f32_16x16x32_bf16 v[104:107], v[158:161], v[196:199], v[104:107]
	v_mfma_f32_16x16x32_bf16 v[92:95], v[140:143], v[200:203], 0
	v_mfma_f32_16x16x32_bf16 v[92:95], v[150:153], v[204:207], v[92:95]
	v_mfma_f32_16x16x32_bf16 v[88:91], v[154:157], v[200:203], 0
	v_mfma_f32_16x16x32_bf16 v[88:91], v[158:161], v[204:207], v[88:91]
	v_mfma_f32_16x16x32_bf16 v[76:79], v[140:143], v[208:211], 0
	v_mfma_f32_16x16x32_bf16 v[76:79], v[150:153], v[212:215], v[76:79]
	v_mfma_f32_16x16x32_bf16 v[72:75], v[154:157], v[208:211], 0
	v_mfma_f32_16x16x32_bf16 v[72:75], v[158:161], v[212:215], v[72:75]
	v_mfma_f32_16x16x32_bf16 v[116:119], v[162:165], v[184:187], 0
	v_mfma_f32_16x16x32_bf16 v[116:119], v[166:169], v[188:191], v[116:119]
	v_mfma_f32_16x16x32_bf16 v[112:115], v[170:173], v[184:187], 0
	v_mfma_f32_16x16x32_bf16 v[112:115], v[174:177], v[188:191], v[112:115]
	v_mfma_f32_16x16x32_bf16 v[100:103], v[162:165], v[192:195], 0
	v_mfma_f32_16x16x32_bf16 v[100:103], v[166:169], v[196:199], v[100:103]
	v_mfma_f32_16x16x32_bf16 v[96:99], v[170:173], v[192:195], 0
	v_mfma_f32_16x16x32_bf16 v[96:99], v[174:177], v[196:199], v[96:99]
	v_mfma_f32_16x16x32_bf16 v[84:87], v[162:165], v[200:203], 0
	v_mfma_f32_16x16x32_bf16 v[84:87], v[166:169], v[204:207], v[84:87]
	v_mfma_f32_16x16x32_bf16 v[80:83], v[170:173], v[200:203], 0
	v_mfma_f32_16x16x32_bf16 v[80:83], v[174:177], v[204:207], v[80:83]
	v_mfma_f32_16x16x32_bf16 v[68:71], v[162:165], v[208:211], 0
	v_mfma_f32_16x16x32_bf16 v[68:71], v[166:169], v[212:215], v[68:71]
	s_barrier
	v_mfma_f32_16x16x32_bf16 v[64:67], v[170:173], v[208:211], 0
	v_mfma_f32_16x16x32_bf16 v[64:67], v[174:177], v[212:215], v[64:67]
	s_setprio 0
	s_add_i32 s75, s66, s58
	v_lshl_add_u64 v[178:179], s[52:53], 0, v[130:131]
	s_mov_b32 m0, s75
	ds_read_b128 v[184:187], v149 offset:16384
	ds_read_b128 v[188:191], v149 offset:17408
	ds_read_b128 v[192:195], v149 offset:18432
	ds_read_b128 v[196:199], v149 offset:19456
	ds_read_b128 v[200:203], v149 offset:20480
	ds_read_b128 v[204:207], v149 offset:21504
	ds_read_b128 v[208:211], v149 offset:22528
	ds_read_b128 v[212:215], v149 offset:23552
	global_load_lds_dwordx4 v[178:179], off
	s_add_i32 m0, s75, 0x2000
	s_add_u32 s76, s52, 0x40000
	v_lshl_add_u64 v[216:217], s[52:53], 0, v[128:129]
	s_addc_u32 s77, s53, 0
	s_add_i32 s75, s67, s58
	global_load_lds_dwordx4 v[216:217], off
	v_lshl_add_u64 v[218:219], s[76:77], 0, v[130:131]
	s_mov_b32 m0, s75
	v_lshl_add_u64 v[220:221], s[54:55], 0, v[128:129]
	global_load_lds_dwordx4 v[218:219], off
	v_lshl_add_u64 v[218:219], s[76:77], 0, v[128:129]
	s_add_i32 m0, s75, 0x2000
	s_nop 0
	global_load_lds_dwordx4 v[218:219], off
	v_lshl_add_u64 v[218:219], s[54:55], 0, v[130:131]
	s_mov_b32 m0, s47
	s_nop 0
	global_load_lds_dwordx4 v[218:219], off
	s_mov_b32 m0, s60
	s_nop 0
	global_load_lds_dwordx4 v[220:221], off
	s_waitcnt vmcnt(8)
	s_waitcnt lgkmcnt(0)
	s_barrier
	s_waitcnt lgkmcnt(0)
	v_mfma_f32_16x16x32_bf16 v[60:63], v[140:143], v[184:187], 0
	v_mfma_f32_16x16x32_bf16 v[60:63], v[150:153], v[188:191], v[60:63]
	s_setprio 1
	v_mfma_f32_16x16x32_bf16 v[56:59], v[154:157], v[184:187], 0
	v_mfma_f32_16x16x32_bf16 v[56:59], v[158:161], v[188:191], v[56:59]
	v_mfma_f32_16x16x32_bf16 v[44:47], v[140:143], v[192:195], 0
	v_mfma_f32_16x16x32_bf16 v[44:47], v[150:153], v[196:199], v[44:47]
	v_mfma_f32_16x16x32_bf16 v[40:43], v[154:157], v[192:195], 0
	v_mfma_f32_16x16x32_bf16 v[40:43], v[158:161], v[196:199], v[40:43]
	v_mfma_f32_16x16x32_bf16 v[28:31], v[140:143], v[200:203], 0
	v_mfma_f32_16x16x32_bf16 v[28:31], v[150:153], v[204:207], v[28:31]
	v_mfma_f32_16x16x32_bf16 v[24:27], v[154:157], v[200:203], 0
	v_mfma_f32_16x16x32_bf16 v[24:27], v[158:161], v[204:207], v[24:27]
	v_mfma_f32_16x16x32_bf16 v[12:15], v[140:143], v[208:211], 0
	v_mfma_f32_16x16x32_bf16 v[12:15], v[150:153], v[212:215], v[12:15]
	v_mfma_f32_16x16x32_bf16 v[8:11], v[154:157], v[208:211], 0
	v_mfma_f32_16x16x32_bf16 v[8:11], v[158:161], v[212:215], v[8:11]
	v_mfma_f32_16x16x32_bf16 v[52:55], v[162:165], v[184:187], 0
	v_mfma_f32_16x16x32_bf16 v[52:55], v[166:169], v[188:191], v[52:55]
	v_mfma_f32_16x16x32_bf16 v[48:51], v[170:173], v[184:187], 0
	v_mfma_f32_16x16x32_bf16 v[48:51], v[174:177], v[188:191], v[48:51]
	v_mfma_f32_16x16x32_bf16 v[36:39], v[162:165], v[192:195], 0
	v_mfma_f32_16x16x32_bf16 v[36:39], v[166:169], v[196:199], v[36:39]
	v_mfma_f32_16x16x32_bf16 v[32:35], v[170:173], v[192:195], 0
	v_mfma_f32_16x16x32_bf16 v[32:35], v[174:177], v[196:199], v[32:35]
	v_mfma_f32_16x16x32_bf16 v[20:23], v[162:165], v[200:203], 0
	v_mfma_f32_16x16x32_bf16 v[20:23], v[166:169], v[204:207], v[20:23]
	v_mfma_f32_16x16x32_bf16 v[16:19], v[170:173], v[200:203], 0
	v_mfma_f32_16x16x32_bf16 v[16:19], v[174:177], v[204:207], v[16:19]
	v_mfma_f32_16x16x32_bf16 v[4:7], v[162:165], v[208:211], 0
	v_mfma_f32_16x16x32_bf16 v[4:7], v[166:169], v[212:215], v[4:7]
	s_barrier
	v_mfma_f32_16x16x32_bf16 v[0:3], v[170:173], v[208:211], 0
	v_mfma_f32_16x16x32_bf16 v[0:3], v[174:177], v[212:215], v[0:3]
	s_setprio 0
	s_branch .Lmid_gemm4

.Lmid_gemm4:
	s_add_i32 s75, 0, 0x18000
	s_add_i32 s76, 0, 0x1c000
	v_add_u32_e32 v158, s75, v145
	v_add_u32_e32 v174, s76, v145
	ds_read_b128 v[140:143], v158
	ds_read_b128 v[150:153], v158 offset:1024
	ds_read_b128 v[154:157], v158 offset:2048
	ds_read_b128 v[158:161], v158 offset:3072
	ds_read_b128 v[162:165], v174
	ds_read_b128 v[166:169], v174 offset:1024
	ds_read_b128 v[170:173], v174 offset:2048
	ds_read_b128 v[174:177], v174 offset:3072
	s_add_u32 s54, s54, 0x40000
	s_addc_u32 s55, s55, 0
	s_mov_b32 m0, s61
	v_lshl_add_u64 v[222:223], s[54:55], 0, v[130:131]
	ds_read_b128 v[184:187], v149 offset:32768
	ds_read_b128 v[188:191], v149 offset:33792
	ds_read_b128 v[192:195], v149 offset:34816
	ds_read_b128 v[196:199], v149 offset:35840
	ds_read_b128 v[200:203], v149 offset:36864
	ds_read_b128 v[204:207], v149 offset:37888
	ds_read_b128 v[208:211], v149 offset:38912
	ds_read_b128 v[212:215], v149 offset:39936
	global_load_lds_dwordx4 v[222:223], off
	v_lshl_add_u64 v[222:223], s[54:55], 0, v[128:129]
	s_mov_b32 m0, s62
	s_nop 0
	global_load_lds_dwordx4 v[222:223], off
	s_waitcnt vmcnt(8)
	s_waitcnt lgkmcnt(0)
	s_barrier
	s_waitcnt lgkmcnt(0)
	v_mfma_f32_16x16x32_bf16 v[124:127], v[140:143], v[184:187], v[124:127]
	v_mfma_f32_16x16x32_bf16 v[124:127], v[150:153], v[188:191], v[124:127]
	s_setprio 1
	v_mfma_f32_16x16x32_bf16 v[120:123], v[154:157], v[184:187], v[120:123]
	v_mfma_f32_16x16x32_bf16 v[120:123], v[158:161], v[188:191], v[120:123]
	v_mfma_f32_16x16x32_bf16 v[108:111], v[140:143], v[192:195], v[108:111]
	v_mfma_f32_16x16x32_bf16 v[108:111], v[150:153], v[196:199], v[108:111]
	v_mfma_f32_16x16x32_bf16 v[104:107], v[154:157], v[192:195], v[104:107]
	v_mfma_f32_16x16x32_bf16 v[104:107], v[158:161], v[196:199], v[104:107]
	v_mfma_f32_16x16x32_bf16 v[92:95], v[140:143], v[200:203], v[92:95]
	v_mfma_f32_16x16x32_bf16 v[92:95], v[150:153], v[204:207], v[92:95]
	v_mfma_f32_16x16x32_bf16 v[88:91], v[154:157], v[200:203], v[88:91]
	v_mfma_f32_16x16x32_bf16 v[88:91], v[158:161], v[204:207], v[88:91]
	v_mfma_f32_16x16x32_bf16 v[76:79], v[140:143], v[208:211], v[76:79]
	v_mfma_f32_16x16x32_bf16 v[76:79], v[150:153], v[212:215], v[76:79]
	v_mfma_f32_16x16x32_bf16 v[72:75], v[154:157], v[208:211], v[72:75]
	v_mfma_f32_16x16x32_bf16 v[72:75], v[158:161], v[212:215], v[72:75]
	v_mfma_f32_16x16x32_bf16 v[116:119], v[162:165], v[184:187], v[116:119]
	v_mfma_f32_16x16x32_bf16 v[116:119], v[166:169], v[188:191], v[116:119]
	v_mfma_f32_16x16x32_bf16 v[112:115], v[170:173], v[184:187], v[112:115]
	v_mfma_f32_16x16x32_bf16 v[112:115], v[174:177], v[188:191], v[112:115]
	v_mfma_f32_16x16x32_bf16 v[100:103], v[162:165], v[192:195], v[100:103]
	v_mfma_f32_16x16x32_bf16 v[100:103], v[166:169], v[196:199], v[100:103]
	v_mfma_f32_16x16x32_bf16 v[96:99], v[170:173], v[192:195], v[96:99]
	v_mfma_f32_16x16x32_bf16 v[96:99], v[174:177], v[196:199], v[96:99]
	v_mfma_f32_16x16x32_bf16 v[84:87], v[162:165], v[200:203], v[84:87]
	v_mfma_f32_16x16x32_bf16 v[84:87], v[166:169], v[204:207], v[84:87]
	v_mfma_f32_16x16x32_bf16 v[80:83], v[170:173], v[200:203], v[80:83]
	v_mfma_f32_16x16x32_bf16 v[80:83], v[174:177], v[204:207], v[80:83]
	v_mfma_f32_16x16x32_bf16 v[68:71], v[162:165], v[208:211], v[68:71]
	v_mfma_f32_16x16x32_bf16 v[68:71], v[166:169], v[212:215], v[68:71]
	s_barrier
	v_mfma_f32_16x16x32_bf16 v[64:67], v[170:173], v[208:211], v[64:67]
	v_mfma_f32_16x16x32_bf16 v[64:67], v[174:177], v[212:215], v[64:67]
	s_setprio 0
	s_add_i32 s54, s75, s58
	v_lshl_add_u64 v[178:179], v[178:179], 0, s[12:13]
	s_mov_b32 m0, s54
	ds_read_b128 v[184:187], v149 offset:49152
	ds_read_b128 v[188:191], v149 offset:50176
	ds_read_b128 v[192:195], v149 offset:51200
	ds_read_b128 v[196:199], v149 offset:52224
	ds_read_b128 v[200:203], v149 offset:53248
	ds_read_b128 v[204:207], v149 offset:54272
	ds_read_b128 v[208:211], v149 offset:55296
	ds_read_b128 v[212:215], v149 offset:56320
	global_load_lds_dwordx4 v[178:179], off
	s_add_i32 m0, s54, 0x2000
	s_add_u32 s52, s52, 0x40080
	v_lshl_add_u64 v[178:179], v[216:217], 0, s[12:13]
	s_addc_u32 s53, s53, 0
	s_add_i32 s54, s76, s58
	global_load_lds_dwordx4 v[178:179], off
	v_lshl_add_u64 v[178:179], s[52:53], 0, v[130:131]
	s_mov_b32 m0, s54
	s_nop 0
	global_load_lds_dwordx4 v[178:179], off
	v_lshl_add_u64 v[178:179], s[52:53], 0, v[128:129]
	s_add_i32 m0, s54, 0x2000
	s_nop 0
	global_load_lds_dwordx4 v[178:179], off
	v_lshl_add_u64 v[178:179], v[218:219], 0, s[12:13]
	s_mov_b32 m0, s64
	s_nop 0
	global_load_lds_dwordx4 v[178:179], off
	v_lshl_add_u64 v[178:179], v[220:221], 0, s[12:13]
	s_mov_b32 m0, s65
	s_nop 0
	global_load_lds_dwordx4 v[178:179], off
	s_waitcnt vmcnt(8)
	s_waitcnt lgkmcnt(0)
	s_barrier
	s_waitcnt lgkmcnt(0)
	v_mfma_f32_16x16x32_bf16 v[60:63], v[140:143], v[184:187], v[60:63]
	v_mfma_f32_16x16x32_bf16 v[60:63], v[150:153], v[188:191], v[60:63]
	s_setprio 1
	v_mfma_f32_16x16x32_bf16 v[56:59], v[154:157], v[184:187], v[56:59]
	v_mfma_f32_16x16x32_bf16 v[56:59], v[158:161], v[188:191], v[56:59]
	v_mfma_f32_16x16x32_bf16 v[44:47], v[140:143], v[192:195], v[44:47]
	v_mfma_f32_16x16x32_bf16 v[44:47], v[150:153], v[196:199], v[44:47]
	v_mfma_f32_16x16x32_bf16 v[40:43], v[154:157], v[192:195], v[40:43]
	v_mfma_f32_16x16x32_bf16 v[40:43], v[158:161], v[196:199], v[40:43]
	v_mfma_f32_16x16x32_bf16 v[28:31], v[140:143], v[200:203], v[28:31]
	v_mfma_f32_16x16x32_bf16 v[28:31], v[150:153], v[204:207], v[28:31]
	v_mfma_f32_16x16x32_bf16 v[24:27], v[154:157], v[200:203], v[24:27]
	v_mfma_f32_16x16x32_bf16 v[24:27], v[158:161], v[204:207], v[24:27]
	v_mfma_f32_16x16x32_bf16 v[12:15], v[140:143], v[208:211], v[12:15]
	v_mfma_f32_16x16x32_bf16 v[12:15], v[150:153], v[212:215], v[12:15]
	v_mfma_f32_16x16x32_bf16 v[8:11], v[154:157], v[208:211], v[8:11]
	v_mfma_f32_16x16x32_bf16 v[8:11], v[158:161], v[212:215], v[8:11]
	v_mfma_f32_16x16x32_bf16 v[52:55], v[162:165], v[184:187], v[52:55]
	v_mfma_f32_16x16x32_bf16 v[52:55], v[166:169], v[188:191], v[52:55]
	v_mfma_f32_16x16x32_bf16 v[48:51], v[170:173], v[184:187], v[48:51]
	v_mfma_f32_16x16x32_bf16 v[48:51], v[174:177], v[188:191], v[48:51]
	v_mfma_f32_16x16x32_bf16 v[36:39], v[162:165], v[192:195], v[36:39]
	v_mfma_f32_16x16x32_bf16 v[36:39], v[166:169], v[196:199], v[36:39]
	v_mfma_f32_16x16x32_bf16 v[32:35], v[170:173], v[192:195], v[32:35]
	v_mfma_f32_16x16x32_bf16 v[32:35], v[174:177], v[196:199], v[32:35]
	v_mfma_f32_16x16x32_bf16 v[20:23], v[162:165], v[200:203], v[20:23]
	v_mfma_f32_16x16x32_bf16 v[20:23], v[166:169], v[204:207], v[20:23]
	v_mfma_f32_16x16x32_bf16 v[16:19], v[170:173], v[200:203], v[16:19]
	v_mfma_f32_16x16x32_bf16 v[16:19], v[174:177], v[204:207], v[16:19]
	v_mfma_f32_16x16x32_bf16 v[4:7], v[162:165], v[208:211], v[4:7]
	v_mfma_f32_16x16x32_bf16 v[4:7], v[166:169], v[212:215], v[4:7]
	s_barrier
	v_mfma_f32_16x16x32_bf16 v[0:3], v[170:173], v[208:211], v[0:3]
	v_mfma_f32_16x16x32_bf16 v[0:3], v[174:177], v[212:215], v[0:3]
	s_setprio 0
	s_add_i32 s74, s74, 2
	s_add_u32 s48, s48, 0x100
	s_addc_u32 s49, s49, 0
	s_add_u32 s72, s72, 0x100
	s_addc_u32 s73, s73, 0
	s_cmp_gt_u32 s74, 13
	s_cbranch_scc0 .LBB0_724
	s_and_b64 vcc, s[16:17], s[10:11]
	s_and_b64 vcc, vcc, exec
	s_cbranch_vccnz .Lpre_4
	s_and_b64 vcc, exec, s[16:17]
	s_cbranch_vccz .LBB0_727
	s_barrier

.Lpre_7:
	s_mov_b32 s98, s71
	s_mov_b32 s100, s48
	s_mov_b32 s71, s18
	s_mov_b32 s48, s36
	s_mov_b64 s[54:55], s[46:47]
	s_mov_b64 s[52:53], s[44:45]
	s_add_i32 s65, s65, 1
	s_mul_i32 s10, s65, s21
	s_mul_hi_u32 s11, s65, s20
	s_add_i32 s11, s11, s10
	s_mul_i32 s10, s65, s20
	s_add_u32 s44, s10, s2
	s_addc_u32 s45, s11, s3
	v_cmp_gt_i64_e32 vcc, s[44:45], v[138:139]
	v_cmp_lt_i64_e64 s[10:11], s[44:45], v[136:137]
	s_cbranch_vccnz .LBB0_950_pk7
	s_lshr_b32 s18, s44, 3
	s_and_b32 s36, s44, 7
	s_lshl_b32 s36, s36, 1
	s_cmp_ge_u32 s18, 0xb0
	s_cbranch_scc0 .Ldec_7_pk7
	s_sub_u32 s18, s18, 0xb0
	s_add_u32 s36, s36, 1

.LBB0_950_pk7:
	s_ashr_i32 s37, s36, 31
	s_lshl_b64 s[44:45], s[36:37], 19
	s_add_u32 s44, s80, s44
	s_addc_u32 s45, s81, s45
	s_and_b64 s[46:47], s[10:11], exec
	s_cselect_b32 s37, s45, s53
	s_cselect_b32 s72, s44, s52
	s_ashr_i32 s19, s18, 31
	s_lshl_b64 s[46:47], s[18:19], 19
	s_add_u32 s46, s58, s46
	s_addc_u32 s47, s59, s47
	s_and_b64 s[56:57], s[10:11], exec
	s_cselect_b32 s19, s47, s55
	s_cselect_b32 s73, s46, s54
	s_add_u32 s52, s52, 0x40080
	s_addc_u32 s53, s53, 0
	s_add_u32 s74, s54, 0x100
	s_addc_u32 s75, s55, 0
	s_mov_b32 s76, -2
	ds_read_b128 v[140:143], v147
	ds_read_b128 v[150:153], v147 offset:1024
	ds_read_b128 v[154:157], v147 offset:2048
	ds_read_b128 v[158:161], v147 offset:3072
	ds_read_b128 v[162:165], v148
	ds_read_b128 v[166:169], v148 offset:1024
	ds_read_b128 v[170:173], v148 offset:2048
	ds_read_b128 v[174:177], v148 offset:3072
	s_add_u32 s54, s52, 0xfffc0080
	s_addc_u32 s55, s53, -1
	s_cmp_eq_u32 s76, 12
	s_cselect_b32 s57, s37, s55
	s_cselect_b32 s56, s72, s54
	s_cselect_b32 s55, s19, s75
	s_cselect_b32 s54, s73, s74
	v_lshl_add_u64 v[178:179], s[52:53], 0, v[132:133]
	s_add_i32 m0, s49, 0xc000
	ds_read_b128 v[184:187], v149
	ds_read_b128 v[188:191], v149 offset:1024
	ds_read_b128 v[192:195], v149 offset:2048
	ds_read_b128 v[196:199], v149 offset:3072
	ds_read_b128 v[200:203], v149 offset:4096
	ds_read_b128 v[204:207], v149 offset:5120
	ds_read_b128 v[208:211], v149 offset:6144
	ds_read_b128 v[212:215], v149 offset:7168
	global_load_lds_dwordx4 v[178:179], off
	v_lshl_add_u64 v[178:179], s[52:53], 0, v[134:135]
	s_add_i32 m0, s49, 0xe000
	s_nop 0
	global_load_lds_dwordx4 v[178:179], off
	s_barrier
	v_mul_f32_e32 v221, 0xbfb8aa3b, v124
	v_exp_f32_e32 v221, v221
	v_mul_f32_e32 v224, 0xbfb8aa3b, v125
	v_exp_f32_e32 v224, v224
	v_lshl_or_b32 v218, s98, 7, v146
	v_add_f32_e32 v221, 1.0, v221
	v_rcp_f32_e32 v221, v221
	v_lshl_add_u32 v220, s100, 8, v144
	v_ashrrev_i32_e32 v219, 31, v218
	v_mov_b64_e32 v[216:217], s[22:23]
	v_mul_f32_e32 v124, v124, v221
	v_mul_f32_e32 v120, v120, v124
	v_add_f32_e32 v124, 1.0, v224
	v_mul_f32_e32 v221, 0xbfb8aa3b, v126
	v_rcp_f32_e32 v124, v124
	v_exp_f32_e32 v221, v221
	v_mul_f32_e32 v224, 0xbfb8aa3b, v127
	v_exp_f32_e32 v224, v224
	v_mul_f32_e32 v124, v125, v124
	v_add_f32_e32 v125, 1.0, v221
	v_rcp_f32_e32 v125, v125
	v_add_f32_e32 v221, 1.0, v224
	v_rcp_f32_e32 v221, v221
	v_mul_f32_e32 v121, v121, v124
	v_mul_f32_e32 v124, v126, v125
	v_mul_f32_e32 v125, 0xbfb8aa3b, v116
	v_exp_f32_e32 v125, v125
	v_mul_f32_e32 v122, v122, v124
	v_mul_f32_e32 v124, v127, v221
	v_mul_f32_e32 v123, v123, v124
	v_cvt_pk_bf16_f32 v120, v120, v121
	v_cvt_pk_bf16_f32 v121, v122, v123
	v_add_f32_e32 v122, 1.0, v125
	v_rcp_f32_e32 v122, v122
	v_mul_f32_e32 v123, 0xbfb8aa3b, v117
	v_exp_f32_e32 v123, v123
	v_mad_i64_i32 v[222:223], vcc, v220, s70, v[216:217]
	v_lshlrev_b64 v[218:219], 1, v[218:219]
	v_lshl_add_u64 v[222:223], v[222:223], 0, v[218:219]
	v_mul_f32_e32 v116, v116, v122
	global_store_dwordx2 v[222:223], v[120:121], off
	v_mul_f32_e32 v112, v112, v116
	v_add_f32_e32 v116, 1.0, v123
	v_mul_f32_e32 v120, 0xbfb8aa3b, v118
	v_rcp_f32_e32 v116, v116
	v_exp_f32_e32 v120, v120
	v_mul_f32_e32 v121, 0xbfb8aa3b, v119
	v_exp_f32_e32 v121, v121
	v_mul_f32_e32 v116, v117, v116
	v_add_f32_e32 v117, 1.0, v120
	v_rcp_f32_e32 v117, v117
	v_add_f32_e32 v120, 1.0, v121
	v_rcp_f32_e32 v120, v120
	v_mul_f32_e32 v113, v113, v116
	v_mul_f32_e32 v116, v118, v117
	v_mul_f32_e32 v114, v114, v116
	v_mul_f32_e32 v116, v119, v120
	v_cvt_pk_bf16_f32 v112, v112, v113
	v_mul_f32_e32 v115, v115, v116
	v_cvt_pk_bf16_f32 v113, v114, v115
	global_store_dwordx2 v[222:223], v[112:113], off offset:128
	v_mul_f32_e32 v112, 0xbfb8aa3b, v108
	v_exp_f32_e32 v114, v112
	v_mul_f32_e32 v115, 0xbfb8aa3b, v109
	v_exp_f32_e32 v115, v115
	v_or_b32_e32 v112, 16, v220
	v_add_f32_e32 v114, 1.0, v114
	v_rcp_f32_e32 v114, v114
	v_mad_i64_i32 v[112:113], vcc, v112, s70, v[216:217]
	v_lshl_add_u64 v[112:113], v[112:113], 0, v[218:219]
	v_mul_f32_e32 v108, v108, v114
	v_mul_f32_e32 v104, v104, v108
	v_add_f32_e32 v108, 1.0, v115
	v_mul_f32_e32 v114, 0xbfb8aa3b, v110
	v_rcp_f32_e32 v108, v108
	v_exp_f32_e32 v114, v114
	v_mul_f32_e32 v115, 0xbfb8aa3b, v111
	v_exp_f32_e32 v115, v115
	v_mul_f32_e32 v108, v109, v108
	v_add_f32_e32 v109, 1.0, v114
	v_rcp_f32_e32 v109, v109
	v_add_f32_e32 v114, 1.0, v115
	v_rcp_f32_e32 v114, v114
	v_mul_f32_e32 v105, v105, v108
	v_mul_f32_e32 v108, v110, v109
	v_mul_f32_e32 v109, 0xbfb8aa3b, v100
	v_exp_f32_e32 v109, v109
	v_mul_f32_e32 v106, v106, v108
	v_mul_f32_e32 v108, v111, v114
	v_mul_f32_e32 v107, v107, v108
	v_cvt_pk_bf16_f32 v104, v104, v105
	v_cvt_pk_bf16_f32 v105, v106, v107
	v_add_f32_e32 v106, 1.0, v109
	v_rcp_f32_e32 v106, v106
	v_mul_f32_e32 v107, 0xbfb8aa3b, v101
	v_exp_f32_e32 v107, v107
	global_store_dwordx2 v[112:113], v[104:105], off
	v_mul_f32_e32 v100, v100, v106
	v_mul_f32_e32 v96, v96, v100
	v_add_f32_e32 v100, 1.0, v107
	v_mul_f32_e32 v104, 0xbfb8aa3b, v102
	v_rcp_f32_e32 v100, v100
	v_exp_f32_e32 v104, v104
	v_mul_f32_e32 v105, 0xbfb8aa3b, v103
	v_exp_f32_e32 v105, v105
	v_mul_f32_e32 v100, v101, v100
	v_add_f32_e32 v101, 1.0, v104
	v_rcp_f32_e32 v101, v101
	v_add_f32_e32 v104, 1.0, v105
	v_rcp_f32_e32 v104, v104
	v_mul_f32_e32 v97, v97, v100
	v_mul_f32_e32 v100, v102, v101
	v_mul_f32_e32 v98, v98, v100
	v_mul_f32_e32 v100, v103, v104
	v_cvt_pk_bf16_f32 v96, v96, v97
	v_mul_f32_e32 v99, v99, v100
	v_cvt_pk_bf16_f32 v97, v98, v99
	global_store_dwordx2 v[112:113], v[96:97], off offset:128
	v_mul_f32_e32 v96, 0xbfb8aa3b, v92
	v_exp_f32_e32 v98, v96
	v_mul_f32_e32 v99, 0xbfb8aa3b, v93
	v_exp_f32_e32 v99, v99
	v_or_b32_e32 v96, 32, v220
	v_add_f32_e32 v98, 1.0, v98
	v_rcp_f32_e32 v98, v98
	v_mad_i64_i32 v[96:97], vcc, v96, s70, v[216:217]
	v_lshl_add_u64 v[96:97], v[96:97], 0, v[218:219]
	v_mul_f32_e32 v92, v92, v98
	v_mul_f32_e32 v88, v88, v92
	v_add_f32_e32 v92, 1.0, v99
	v_mul_f32_e32 v98, 0xbfb8aa3b, v94
	v_rcp_f32_e32 v92, v92
	v_exp_f32_e32 v98, v98
	v_mul_f32_e32 v99, 0xbfb8aa3b, v95
	v_exp_f32_e32 v99, v99
	v_mul_f32_e32 v92, v93, v92
	v_add_f32_e32 v93, 1.0, v98
	v_rcp_f32_e32 v93, v93
	v_add_f32_e32 v98, 1.0, v99
	v_rcp_f32_e32 v98, v98
	v_mul_f32_e32 v89, v89, v92
	v_mul_f32_e32 v92, v94, v93
	v_mul_f32_e32 v93, 0xbfb8aa3b, v84
	v_exp_f32_e32 v93, v93
	v_mul_f32_e32 v90, v90, v92
	v_mul_f32_e32 v92, v95, v98
	v_mul_f32_e32 v91, v91, v92
	v_cvt_pk_bf16_f32 v88, v88, v89
	v_cvt_pk_bf16_f32 v89, v90, v91
	v_add_f32_e32 v90, 1.0, v93
	v_rcp_f32_e32 v90, v90
	v_mul_f32_e32 v91, 0xbfb8aa3b, v85
	v_exp_f32_e32 v91, v91
	global_store_dwordx2 v[96:97], v[88:89], off
	v_mul_f32_e32 v84, v84, v90
	v_mul_f32_e32 v80, v80, v84
	v_add_f32_e32 v84, 1.0, v91
	v_mul_f32_e32 v88, 0xbfb8aa3b, v86
	v_rcp_f32_e32 v84, v84
	v_exp_f32_e32 v88, v88
	v_mul_f32_e32 v89, 0xbfb8aa3b, v87
	v_exp_f32_e32 v89, v89
	v_mul_f32_e32 v84, v85, v84
	v_add_f32_e32 v85, 1.0, v88
	v_rcp_f32_e32 v85, v85
	v_add_f32_e32 v88, 1.0, v89
	v_rcp_f32_e32 v88, v88
	v_mul_f32_e32 v81, v81, v84
	v_mul_f32_e32 v84, v86, v85
	v_mul_f32_e32 v82, v82, v84
	v_mul_f32_e32 v84, v87, v88
	v_cvt_pk_bf16_f32 v80, v80, v81
	v_mul_f32_e32 v83, v83, v84
	v_cvt_pk_bf16_f32 v81, v82, v83
	global_store_dwordx2 v[96:97], v[80:81], off offset:128
	v_mul_f32_e32 v80, 0xbfb8aa3b, v76
	v_exp_f32_e32 v82, v80
	v_mul_f32_e32 v83, 0xbfb8aa3b, v77
	v_exp_f32_e32 v83, v83
	v_or_b32_e32 v80, 48, v220
	v_add_f32_e32 v82, 1.0, v82
	v_rcp_f32_e32 v82, v82
	v_mad_i64_i32 v[80:81], vcc, v80, s70, v[216:217]
	v_lshl_add_u64 v[80:81], v[80:81], 0, v[218:219]
	v_mul_f32_e32 v76, v76, v82
	v_mul_f32_e32 v72, v72, v76
	v_add_f32_e32 v76, 1.0, v83
	v_mul_f32_e32 v82, 0xbfb8aa3b, v78
	v_rcp_f32_e32 v76, v76
	v_exp_f32_e32 v82, v82
	v_mul_f32_e32 v83, 0xbfb8aa3b, v79
	v_exp_f32_e32 v83, v83
	v_mul_f32_e32 v76, v77, v76
	v_add_f32_e32 v77, 1.0, v82
	v_rcp_f32_e32 v77, v77
	v_add_f32_e32 v82, 1.0, v83
	v_rcp_f32_e32 v82, v82
	v_mul_f32_e32 v73, v73, v76
	v_mul_f32_e32 v76, v78, v77
	v_mul_f32_e32 v77, 0xbfb8aa3b, v68
	v_exp_f32_e32 v77, v77
	v_mul_f32_e32 v74, v74, v76
	v_mul_f32_e32 v76, v79, v82
	v_mul_f32_e32 v75, v75, v76
	v_cvt_pk_bf16_f32 v72, v72, v73
	v_cvt_pk_bf16_f32 v73, v74, v75
	v_add_f32_e32 v74, 1.0, v77
	v_rcp_f32_e32 v74, v74
	v_mul_f32_e32 v75, 0xbfb8aa3b, v69
	v_exp_f32_e32 v75, v75
	global_store_dwordx2 v[80:81], v[72:73], off
	v_mul_f32_e32 v68, v68, v74
	v_mul_f32_e32 v64, v64, v68
	v_add_f32_e32 v68, 1.0, v75
	v_mul_f32_e32 v72, 0xbfb8aa3b, v70
	v_rcp_f32_e32 v68, v68
	v_exp_f32_e32 v72, v72
	v_mul_f32_e32 v73, 0xbfb8aa3b, v71
	v_exp_f32_e32 v73, v73
	v_mul_f32_e32 v68, v69, v68
	v_add_f32_e32 v69, 1.0, v72
	v_rcp_f32_e32 v69, v69
	v_add_f32_e32 v72, 1.0, v73
	v_rcp_f32_e32 v72, v72
	v_mul_f32_e32 v65, v65, v68
	v_mul_f32_e32 v68, v70, v69
	v_mul_f32_e32 v66, v66, v68
	v_mul_f32_e32 v68, v71, v72
	v_cvt_pk_bf16_f32 v64, v64, v65
	v_mul_f32_e32 v67, v67, v68
	v_cvt_pk_bf16_f32 v65, v66, v67
	global_store_dwordx2 v[80:81], v[64:65], off offset:128
	v_mul_f32_e32 v64, 0xbfb8aa3b, v60
	v_exp_f32_e32 v66, v64
	v_mul_f32_e32 v67, 0xbfb8aa3b, v61
	v_exp_f32_e32 v67, v67
	v_add_u32_e32 v64, 0x80, v220
	v_add_f32_e32 v66, 1.0, v66
	v_rcp_f32_e32 v66, v66
	v_mad_i64_i32 v[64:65], vcc, v64, s70, v[216:217]
	v_lshl_add_u64 v[64:65], v[64:65], 0, v[218:219]
	v_mul_f32_e32 v60, v60, v66
	v_mul_f32_e32 v56, v56, v60
	v_add_f32_e32 v60, 1.0, v67
	v_mul_f32_e32 v66, 0xbfb8aa3b, v62
	v_rcp_f32_e32 v60, v60
	v_exp_f32_e32 v66, v66
	v_mul_f32_e32 v67, 0xbfb8aa3b, v63
	v_exp_f32_e32 v67, v67
	v_mul_f32_e32 v60, v61, v60
	v_add_f32_e32 v61, 1.0, v66
	v_rcp_f32_e32 v61, v61
	v_add_f32_e32 v66, 1.0, v67
	v_rcp_f32_e32 v66, v66
	v_mul_f32_e32 v57, v57, v60
	v_mul_f32_e32 v60, v62, v61
	v_mul_f32_e32 v61, 0xbfb8aa3b, v52
	v_exp_f32_e32 v61, v61
	v_mul_f32_e32 v58, v58, v60
	v_mul_f32_e32 v60, v63, v66
	v_mul_f32_e32 v59, v59, v60
	v_cvt_pk_bf16_f32 v56, v56, v57
	v_cvt_pk_bf16_f32 v57, v58, v59
	v_add_f32_e32 v58, 1.0, v61
	v_rcp_f32_e32 v58, v58
	v_mul_f32_e32 v59, 0xbfb8aa3b, v53
	v_exp_f32_e32 v59, v59
	global_store_dwordx2 v[64:65], v[56:57], off
	v_mul_f32_e32 v52, v52, v58
	v_mul_f32_e32 v48, v48, v52
	v_add_f32_e32 v52, 1.0, v59
	v_mul_f32_e32 v56, 0xbfb8aa3b, v54
	v_rcp_f32_e32 v52, v52
	v_exp_f32_e32 v56, v56
	v_mul_f32_e32 v57, 0xbfb8aa3b, v55
	v_exp_f32_e32 v57, v57
	v_mul_f32_e32 v52, v53, v52
	v_add_f32_e32 v53, 1.0, v56
	v_rcp_f32_e32 v53, v53
	v_add_f32_e32 v56, 1.0, v57
	v_rcp_f32_e32 v56, v56
	v_mul_f32_e32 v49, v49, v52
	v_mul_f32_e32 v52, v54, v53
	v_mul_f32_e32 v50, v50, v52
	v_mul_f32_e32 v52, v55, v56
	v_cvt_pk_bf16_f32 v48, v48, v49
	v_mul_f32_e32 v51, v51, v52
	v_cvt_pk_bf16_f32 v49, v50, v51
	global_store_dwordx2 v[64:65], v[48:49], off offset:128
	v_mul_f32_e32 v48, 0xbfb8aa3b, v44
	v_exp_f32_e32 v50, v48
	v_mul_f32_e32 v51, 0xbfb8aa3b, v45
	v_exp_f32_e32 v51, v51
	v_add_u32_e32 v48, 0x90, v220
	v_add_f32_e32 v50, 1.0, v50
	v_rcp_f32_e32 v50, v50
	v_mad_i64_i32 v[48:49], vcc, v48, s70, v[216:217]
	v_lshl_add_u64 v[48:49], v[48:49], 0, v[218:219]
	v_mul_f32_e32 v44, v44, v50
	v_mul_f32_e32 v40, v40, v44
	v_add_f32_e32 v44, 1.0, v51
	v_mul_f32_e32 v50, 0xbfb8aa3b, v46
	v_rcp_f32_e32 v44, v44
	v_exp_f32_e32 v50, v50
	v_mul_f32_e32 v51, 0xbfb8aa3b, v47
	v_exp_f32_e32 v51, v51
	v_mul_f32_e32 v44, v45, v44
	v_add_f32_e32 v45, 1.0, v50
	v_rcp_f32_e32 v45, v45
	v_add_f32_e32 v50, 1.0, v51
	v_rcp_f32_e32 v50, v50
	v_mul_f32_e32 v41, v41, v44
	v_mul_f32_e32 v44, v46, v45
	v_mul_f32_e32 v45, 0xbfb8aa3b, v36
	v_exp_f32_e32 v45, v45
	v_mul_f32_e32 v42, v42, v44
	v_mul_f32_e32 v44, v47, v50
	v_mul_f32_e32 v43, v43, v44
	v_cvt_pk_bf16_f32 v40, v40, v41
	v_cvt_pk_bf16_f32 v41, v42, v43
	v_add_f32_e32 v42, 1.0, v45
	v_rcp_f32_e32 v42, v42
	v_mul_f32_e32 v43, 0xbfb8aa3b, v37
	v_exp_f32_e32 v43, v43
	global_store_dwordx2 v[48:49], v[40:41], off
	v_mul_f32_e32 v36, v36, v42
	v_mul_f32_e32 v32, v32, v36
	v_add_f32_e32 v36, 1.0, v43
	v_mul_f32_e32 v40, 0xbfb8aa3b, v38
	v_rcp_f32_e32 v36, v36
	v_exp_f32_e32 v40, v40
	v_mul_f32_e32 v41, 0xbfb8aa3b, v39
	v_exp_f32_e32 v41, v41
	v_mul_f32_e32 v36, v37, v36
	v_add_f32_e32 v37, 1.0, v40
	v_rcp_f32_e32 v37, v37
	v_add_f32_e32 v40, 1.0, v41
	v_rcp_f32_e32 v40, v40
	v_mul_f32_e32 v33, v33, v36
	v_mul_f32_e32 v36, v38, v37
	v_mul_f32_e32 v34, v34, v36
	v_mul_f32_e32 v36, v39, v40
	v_cvt_pk_bf16_f32 v32, v32, v33
	v_mul_f32_e32 v35, v35, v36
	v_cvt_pk_bf16_f32 v33, v34, v35
	global_store_dwordx2 v[48:49], v[32:33], off offset:128
	v_mul_f32_e32 v32, 0xbfb8aa3b, v28
	v_exp_f32_e32 v34, v32
	v_mul_f32_e32 v35, 0xbfb8aa3b, v29
	v_exp_f32_e32 v35, v35
	v_add_u32_e32 v32, 0xa0, v220
	v_add_f32_e32 v34, 1.0, v34
	v_rcp_f32_e32 v34, v34
	v_mad_i64_i32 v[32:33], vcc, v32, s70, v[216:217]
	v_lshl_add_u64 v[32:33], v[32:33], 0, v[218:219]
	v_mul_f32_e32 v28, v28, v34
	v_mul_f32_e32 v24, v24, v28
	v_add_f32_e32 v28, 1.0, v35
	v_mul_f32_e32 v34, 0xbfb8aa3b, v30
	v_rcp_f32_e32 v28, v28
	v_exp_f32_e32 v34, v34
	v_mul_f32_e32 v35, 0xbfb8aa3b, v31
	v_exp_f32_e32 v35, v35
	v_mul_f32_e32 v28, v29, v28
	v_add_f32_e32 v29, 1.0, v34
	v_rcp_f32_e32 v29, v29
	v_add_f32_e32 v34, 1.0, v35
	v_rcp_f32_e32 v34, v34
	v_mul_f32_e32 v25, v25, v28
	v_mul_f32_e32 v28, v30, v29
	v_mul_f32_e32 v29, 0xbfb8aa3b, v20
	v_exp_f32_e32 v29, v29
	v_mul_f32_e32 v26, v26, v28
	v_mul_f32_e32 v28, v31, v34
	v_mul_f32_e32 v27, v27, v28
	v_cvt_pk_bf16_f32 v24, v24, v25
	v_cvt_pk_bf16_f32 v25, v26, v27
	v_add_f32_e32 v26, 1.0, v29
	v_rcp_f32_e32 v26, v26
	v_mul_f32_e32 v27, 0xbfb8aa3b, v21
	v_exp_f32_e32 v27, v27
	global_store_dwordx2 v[32:33], v[24:25], off
	v_mul_f32_e32 v20, v20, v26
	v_mul_f32_e32 v16, v16, v20
	v_add_f32_e32 v20, 1.0, v27
	v_mul_f32_e32 v24, 0xbfb8aa3b, v22
	v_rcp_f32_e32 v20, v20
	v_exp_f32_e32 v24, v24
	v_mul_f32_e32 v25, 0xbfb8aa3b, v23
	v_exp_f32_e32 v25, v25
	v_mul_f32_e32 v20, v21, v20
	v_add_f32_e32 v21, 1.0, v24
	v_rcp_f32_e32 v21, v21
	v_add_f32_e32 v24, 1.0, v25
	v_rcp_f32_e32 v24, v24
	v_mul_f32_e32 v17, v17, v20
	v_mul_f32_e32 v20, v22, v21
	v_mul_f32_e32 v18, v18, v20
	v_mul_f32_e32 v20, v23, v24
	v_cvt_pk_bf16_f32 v16, v16, v17
	v_mul_f32_e32 v19, v19, v20
	v_cvt_pk_bf16_f32 v17, v18, v19
	global_store_dwordx2 v[32:33], v[16:17], off offset:128
	v_mul_f32_e32 v16, 0xbfb8aa3b, v12
	v_exp_f32_e32 v18, v16
	v_mul_f32_e32 v19, 0xbfb8aa3b, v13
	v_exp_f32_e32 v19, v19
	v_add_u32_e32 v16, 0xb0, v220
	v_add_f32_e32 v18, 1.0, v18
	v_rcp_f32_e32 v18, v18
	v_mad_i64_i32 v[16:17], vcc, v16, s70, v[216:217]
	v_lshl_add_u64 v[16:17], v[16:17], 0, v[218:219]
	v_mul_f32_e32 v12, v12, v18
	v_mul_f32_e32 v8, v8, v12
	v_add_f32_e32 v12, 1.0, v19
	v_mul_f32_e32 v18, 0xbfb8aa3b, v14
	v_rcp_f32_e32 v12, v12
	v_exp_f32_e32 v18, v18
	v_mul_f32_e32 v19, 0xbfb8aa3b, v15
	v_exp_f32_e32 v19, v19
	v_mul_f32_e32 v12, v13, v12
	v_add_f32_e32 v13, 1.0, v18
	v_rcp_f32_e32 v13, v13
	v_add_f32_e32 v18, 1.0, v19
	v_rcp_f32_e32 v18, v18
	v_mul_f32_e32 v9, v9, v12
	v_mul_f32_e32 v12, v14, v13
	v_mul_f32_e32 v13, 0xbfb8aa3b, v4
	v_exp_f32_e32 v13, v13
	v_mul_f32_e32 v10, v10, v12
	v_mul_f32_e32 v12, v15, v18
	v_mul_f32_e32 v11, v11, v12
	v_cvt_pk_bf16_f32 v8, v8, v9
	v_cvt_pk_bf16_f32 v9, v10, v11
	v_add_f32_e32 v10, 1.0, v13
	v_rcp_f32_e32 v10, v10
	v_mul_f32_e32 v11, 0xbfb8aa3b, v5
	v_exp_f32_e32 v11, v11
	global_store_dwordx2 v[16:17], v[8:9], off
	v_mul_f32_e32 v4, v4, v10
	v_mul_f32_e32 v0, v0, v4
	v_add_f32_e32 v4, 1.0, v11
	v_mul_f32_e32 v8, 0xbfb8aa3b, v6
	v_rcp_f32_e32 v4, v4
	v_exp_f32_e32 v8, v8
	v_mul_f32_e32 v9, 0xbfb8aa3b, v7
	v_exp_f32_e32 v9, v9
	v_mul_f32_e32 v4, v5, v4
	v_add_f32_e32 v5, 1.0, v8
	v_rcp_f32_e32 v5, v5
	v_add_f32_e32 v8, 1.0, v9
	v_rcp_f32_e32 v8, v8
	v_mul_f32_e32 v1, v1, v4
	v_mul_f32_e32 v4, v6, v5
	v_mul_f32_e32 v2, v2, v4
	v_mul_f32_e32 v4, v7, v8
	v_mul_f32_e32 v3, v3, v4
	v_cvt_pk_bf16_f32 v0, v0, v1
	v_cvt_pk_bf16_f32 v1, v2, v3
	global_store_dwordx2 v[16:17], v[0:1], off offset:128
	s_waitcnt vmcnt(8)
	s_waitcnt lgkmcnt(0)
	s_barrier
	s_waitcnt lgkmcnt(0)
	v_mfma_f32_16x16x32_bf16 v[124:127], v[140:143], v[184:187], 0
	v_mfma_f32_16x16x32_bf16 v[124:127], v[150:153], v[188:191], v[124:127]
	s_setprio 1
	v_mfma_f32_16x16x32_bf16 v[120:123], v[154:157], v[184:187], 0
	v_mfma_f32_16x16x32_bf16 v[120:123], v[158:161], v[188:191], v[120:123]
	v_mfma_f32_16x16x32_bf16 v[108:111], v[140:143], v[192:195], 0
	v_mfma_f32_16x16x32_bf16 v[108:111], v[150:153], v[196:199], v[108:111]
	v_mfma_f32_16x16x32_bf16 v[104:107], v[154:157], v[192:195], 0
	v_mfma_f32_16x16x32_bf16 v[104:107], v[158:161], v[196:199], v[104:107]
	v_mfma_f32_16x16x32_bf16 v[92:95], v[140:143], v[200:203], 0
	v_mfma_f32_16x16x32_bf16 v[92:95], v[150:153], v[204:207], v[92:95]
	v_mfma_f32_16x16x32_bf16 v[88:91], v[154:157], v[200:203], 0
	v_mfma_f32_16x16x32_bf16 v[88:91], v[158:161], v[204:207], v[88:91]
	v_mfma_f32_16x16x32_bf16 v[76:79], v[140:143], v[208:211], 0
	v_mfma_f32_16x16x32_bf16 v[76:79], v[150:153], v[212:215], v[76:79]
	v_mfma_f32_16x16x32_bf16 v[72:75], v[154:157], v[208:211], 0
	v_mfma_f32_16x16x32_bf16 v[72:75], v[158:161], v[212:215], v[72:75]
	v_mfma_f32_16x16x32_bf16 v[116:119], v[162:165], v[184:187], 0
	v_mfma_f32_16x16x32_bf16 v[116:119], v[166:169], v[188:191], v[116:119]
	v_mfma_f32_16x16x32_bf16 v[112:115], v[170:173], v[184:187], 0
	v_mfma_f32_16x16x32_bf16 v[112:115], v[174:177], v[188:191], v[112:115]
	v_mfma_f32_16x16x32_bf16 v[100:103], v[162:165], v[192:195], 0
	v_mfma_f32_16x16x32_bf16 v[100:103], v[166:169], v[196:199], v[100:103]
	v_mfma_f32_16x16x32_bf16 v[96:99], v[170:173], v[192:195], 0
	v_mfma_f32_16x16x32_bf16 v[96:99], v[174:177], v[196:199], v[96:99]
	v_mfma_f32_16x16x32_bf16 v[84:87], v[162:165], v[200:203], 0
	v_mfma_f32_16x16x32_bf16 v[84:87], v[166:169], v[204:207], v[84:87]
	v_mfma_f32_16x16x32_bf16 v[80:83], v[170:173], v[200:203], 0
	v_mfma_f32_16x16x32_bf16 v[80:83], v[174:177], v[204:207], v[80:83]
	v_mfma_f32_16x16x32_bf16 v[68:71], v[162:165], v[208:211], 0
	v_mfma_f32_16x16x32_bf16 v[68:71], v[166:169], v[212:215], v[68:71]
	s_barrier
	v_mfma_f32_16x16x32_bf16 v[64:67], v[170:173], v[208:211], 0
	v_mfma_f32_16x16x32_bf16 v[64:67], v[174:177], v[212:215], v[64:67]
	s_setprio 0
	s_add_i32 s77, s68, s60
	v_lshl_add_u64 v[178:179], s[54:55], 0, v[130:131]
	s_mov_b32 m0, s77
	ds_read_b128 v[184:187], v149 offset:16384
	ds_read_b128 v[188:191], v149 offset:17408
	ds_read_b128 v[192:195], v149 offset:18432
	ds_read_b128 v[196:199], v149 offset:19456
	ds_read_b128 v[200:203], v149 offset:20480
	ds_read_b128 v[204:207], v149 offset:21504
	ds_read_b128 v[208:211], v149 offset:22528
	ds_read_b128 v[212:215], v149 offset:23552
	global_load_lds_dwordx4 v[178:179], off
	s_add_i32 m0, s77, 0x2000
	s_add_u32 s82, s54, 0x40000
	v_lshl_add_u64 v[216:217], s[54:55], 0, v[128:129]
	s_addc_u32 s83, s55, 0
	s_add_i32 s77, s69, s60
	global_load_lds_dwordx4 v[216:217], off
	v_lshl_add_u64 v[218:219], s[82:83], 0, v[130:131]
	s_mov_b32 m0, s77
	v_lshl_add_u64 v[220:221], s[56:57], 0, v[128:129]
	global_load_lds_dwordx4 v[218:219], off
	v_lshl_add_u64 v[218:219], s[82:83], 0, v[128:129]
	s_add_i32 m0, s77, 0x2000
	s_nop 0
	global_load_lds_dwordx4 v[218:219], off
	v_lshl_add_u64 v[218:219], s[56:57], 0, v[130:131]
	s_mov_b32 m0, s49
	s_nop 0
	global_load_lds_dwordx4 v[218:219], off
	s_mov_b32 m0, s62
	s_nop 0
	global_load_lds_dwordx4 v[220:221], off
	s_waitcnt vmcnt(8)
	s_waitcnt lgkmcnt(0)
	s_barrier
	s_waitcnt lgkmcnt(0)
	v_mfma_f32_16x16x32_bf16 v[60:63], v[140:143], v[184:187], 0
	v_mfma_f32_16x16x32_bf16 v[60:63], v[150:153], v[188:191], v[60:63]
	s_setprio 1
	v_mfma_f32_16x16x32_bf16 v[56:59], v[154:157], v[184:187], 0
	v_mfma_f32_16x16x32_bf16 v[56:59], v[158:161], v[188:191], v[56:59]
	v_mfma_f32_16x16x32_bf16 v[44:47], v[140:143], v[192:195], 0
	v_mfma_f32_16x16x32_bf16 v[44:47], v[150:153], v[196:199], v[44:47]
	v_mfma_f32_16x16x32_bf16 v[40:43], v[154:157], v[192:195], 0
	v_mfma_f32_16x16x32_bf16 v[40:43], v[158:161], v[196:199], v[40:43]
	v_mfma_f32_16x16x32_bf16 v[28:31], v[140:143], v[200:203], 0
	v_mfma_f32_16x16x32_bf16 v[28:31], v[150:153], v[204:207], v[28:31]
	v_mfma_f32_16x16x32_bf16 v[24:27], v[154:157], v[200:203], 0
	v_mfma_f32_16x16x32_bf16 v[24:27], v[158:161], v[204:207], v[24:27]
	v_mfma_f32_16x16x32_bf16 v[12:15], v[140:143], v[208:211], 0
	v_mfma_f32_16x16x32_bf16 v[12:15], v[150:153], v[212:215], v[12:15]
	v_mfma_f32_16x16x32_bf16 v[8:11], v[154:157], v[208:211], 0
	v_mfma_f32_16x16x32_bf16 v[8:11], v[158:161], v[212:215], v[8:11]
	v_mfma_f32_16x16x32_bf16 v[52:55], v[162:165], v[184:187], 0
	v_mfma_f32_16x16x32_bf16 v[52:55], v[166:169], v[188:191], v[52:55]
	v_mfma_f32_16x16x32_bf16 v[48:51], v[170:173], v[184:187], 0
	v_mfma_f32_16x16x32_bf16 v[48:51], v[174:177], v[188:191], v[48:51]
	v_mfma_f32_16x16x32_bf16 v[36:39], v[162:165], v[192:195], 0
	v_mfma_f32_16x16x32_bf16 v[36:39], v[166:169], v[196:199], v[36:39]
	v_mfma_f32_16x16x32_bf16 v[32:35], v[170:173], v[192:195], 0
	v_mfma_f32_16x16x32_bf16 v[32:35], v[174:177], v[196:199], v[32:35]
	v_mfma_f32_16x16x32_bf16 v[20:23], v[162:165], v[200:203], 0
	v_mfma_f32_16x16x32_bf16 v[20:23], v[166:169], v[204:207], v[20:23]
	v_mfma_f32_16x16x32_bf16 v[16:19], v[170:173], v[200:203], 0
	v_mfma_f32_16x16x32_bf16 v[16:19], v[174:177], v[204:207], v[16:19]
	v_mfma_f32_16x16x32_bf16 v[4:7], v[162:165], v[208:211], 0
	v_mfma_f32_16x16x32_bf16 v[4:7], v[166:169], v[212:215], v[4:7]
	s_barrier
	v_mfma_f32_16x16x32_bf16 v[0:3], v[170:173], v[208:211], 0
	v_mfma_f32_16x16x32_bf16 v[0:3], v[174:177], v[212:215], v[0:3]
	s_setprio 0
	s_branch .Lmid_gemm7

.Lmid_gemm7:
	s_add_i32 s77, 0, 0x18000
	s_add_i32 s79, 0, 0x1c000
	v_add_u32_e32 v158, s77, v145
	v_add_u32_e32 v174, s79, v145
	ds_read_b128 v[140:143], v158
	ds_read_b128 v[150:153], v158 offset:1024
	ds_read_b128 v[154:157], v158 offset:2048
	ds_read_b128 v[158:161], v158 offset:3072
	ds_read_b128 v[162:165], v174
	ds_read_b128 v[166:169], v174 offset:1024
	ds_read_b128 v[170:173], v174 offset:2048
	ds_read_b128 v[174:177], v174 offset:3072
	s_add_u32 s56, s56, 0x40000
	s_addc_u32 s57, s57, 0
	s_mov_b32 m0, s63
	v_lshl_add_u64 v[222:223], s[56:57], 0, v[130:131]
	ds_read_b128 v[184:187], v149 offset:32768
	ds_read_b128 v[188:191], v149 offset:33792
	ds_read_b128 v[192:195], v149 offset:34816
	ds_read_b128 v[196:199], v149 offset:35840
	ds_read_b128 v[200:203], v149 offset:36864
	ds_read_b128 v[204:207], v149 offset:37888
	ds_read_b128 v[208:211], v149 offset:38912
	ds_read_b128 v[212:215], v149 offset:39936
	global_load_lds_dwordx4 v[222:223], off
	v_lshl_add_u64 v[222:223], s[56:57], 0, v[128:129]
	s_mov_b32 m0, s64
	s_nop 0
	global_load_lds_dwordx4 v[222:223], off
	s_waitcnt vmcnt(8)
	s_waitcnt lgkmcnt(0)
	s_barrier
	s_waitcnt lgkmcnt(0)
	v_mfma_f32_16x16x32_bf16 v[124:127], v[140:143], v[184:187], v[124:127]
	v_mfma_f32_16x16x32_bf16 v[124:127], v[150:153], v[188:191], v[124:127]
	s_setprio 1
	v_mfma_f32_16x16x32_bf16 v[120:123], v[154:157], v[184:187], v[120:123]
	v_mfma_f32_16x16x32_bf16 v[120:123], v[158:161], v[188:191], v[120:123]
	v_mfma_f32_16x16x32_bf16 v[108:111], v[140:143], v[192:195], v[108:111]
	v_mfma_f32_16x16x32_bf16 v[108:111], v[150:153], v[196:199], v[108:111]
	v_mfma_f32_16x16x32_bf16 v[104:107], v[154:157], v[192:195], v[104:107]
	v_mfma_f32_16x16x32_bf16 v[104:107], v[158:161], v[196:199], v[104:107]
	v_mfma_f32_16x16x32_bf16 v[92:95], v[140:143], v[200:203], v[92:95]
	v_mfma_f32_16x16x32_bf16 v[92:95], v[150:153], v[204:207], v[92:95]
	v_mfma_f32_16x16x32_bf16 v[88:91], v[154:157], v[200:203], v[88:91]
	v_mfma_f32_16x16x32_bf16 v[88:91], v[158:161], v[204:207], v[88:91]
	v_mfma_f32_16x16x32_bf16 v[76:79], v[140:143], v[208:211], v[76:79]
	v_mfma_f32_16x16x32_bf16 v[76:79], v[150:153], v[212:215], v[76:79]
	v_mfma_f32_16x16x32_bf16 v[72:75], v[154:157], v[208:211], v[72:75]
	v_mfma_f32_16x16x32_bf16 v[72:75], v[158:161], v[212:215], v[72:75]
	v_mfma_f32_16x16x32_bf16 v[116:119], v[162:165], v[184:187], v[116:119]
	v_mfma_f32_16x16x32_bf16 v[116:119], v[166:169], v[188:191], v[116:119]
	v_mfma_f32_16x16x32_bf16 v[112:115], v[170:173], v[184:187], v[112:115]
	v_mfma_f32_16x16x32_bf16 v[112:115], v[174:177], v[188:191], v[112:115]
	v_mfma_f32_16x16x32_bf16 v[100:103], v[162:165], v[192:195], v[100:103]
	v_mfma_f32_16x16x32_bf16 v[100:103], v[166:169], v[196:199], v[100:103]
	v_mfma_f32_16x16x32_bf16 v[96:99], v[170:173], v[192:195], v[96:99]
	v_mfma_f32_16x16x32_bf16 v[96:99], v[174:177], v[196:199], v[96:99]
	v_mfma_f32_16x16x32_bf16 v[84:87], v[162:165], v[200:203], v[84:87]
	v_mfma_f32_16x16x32_bf16 v[84:87], v[166:169], v[204:207], v[84:87]
	v_mfma_f32_16x16x32_bf16 v[80:83], v[170:173], v[200:203], v[80:83]
	v_mfma_f32_16x16x32_bf16 v[80:83], v[174:177], v[204:207], v[80:83]
	v_mfma_f32_16x16x32_bf16 v[68:71], v[162:165], v[208:211], v[68:71]
	v_mfma_f32_16x16x32_bf16 v[68:71], v[166:169], v[212:215], v[68:71]
	s_barrier
	v_mfma_f32_16x16x32_bf16 v[64:67], v[170:173], v[208:211], v[64:67]
	v_mfma_f32_16x16x32_bf16 v[64:67], v[174:177], v[212:215], v[64:67]
	s_setprio 0
	s_add_i32 s56, s77, s60
	v_lshl_add_u64 v[178:179], v[178:179], 0, s[12:13]
	s_mov_b32 m0, s56
	ds_read_b128 v[184:187], v149 offset:49152
	ds_read_b128 v[188:191], v149 offset:50176
	ds_read_b128 v[192:195], v149 offset:51200
	ds_read_b128 v[196:199], v149 offset:52224
	ds_read_b128 v[200:203], v149 offset:53248
	ds_read_b128 v[204:207], v149 offset:54272
	ds_read_b128 v[208:211], v149 offset:55296
	ds_read_b128 v[212:215], v149 offset:56320
	global_load_lds_dwordx4 v[178:179], off
	s_add_i32 m0, s56, 0x2000
	s_add_u32 s54, s54, 0x40080
	v_lshl_add_u64 v[178:179], v[216:217], 0, s[12:13]
	s_addc_u32 s55, s55, 0
	s_add_i32 s56, s79, s60
	global_load_lds_dwordx4 v[178:179], off
	v_lshl_add_u64 v[178:179], s[54:55], 0, v[130:131]
	s_mov_b32 m0, s56
	s_nop 0
	global_load_lds_dwordx4 v[178:179], off
	v_lshl_add_u64 v[178:179], s[54:55], 0, v[128:129]
	s_add_i32 m0, s56, 0x2000
	s_nop 0
	global_load_lds_dwordx4 v[178:179], off
	v_lshl_add_u64 v[178:179], v[218:219], 0, s[12:13]
	s_mov_b32 m0, s66
	s_nop 0
	global_load_lds_dwordx4 v[178:179], off
	v_lshl_add_u64 v[178:179], v[220:221], 0, s[12:13]
	s_mov_b32 m0, s67
	s_nop 0
	global_load_lds_dwordx4 v[178:179], off
	s_waitcnt vmcnt(8)
	s_waitcnt lgkmcnt(0)
	s_barrier
	s_waitcnt lgkmcnt(0)
	v_mfma_f32_16x16x32_bf16 v[60:63], v[140:143], v[184:187], v[60:63]
	v_mfma_f32_16x16x32_bf16 v[60:63], v[150:153], v[188:191], v[60:63]
	s_setprio 1
	v_mfma_f32_16x16x32_bf16 v[56:59], v[154:157], v[184:187], v[56:59]
	v_mfma_f32_16x16x32_bf16 v[56:59], v[158:161], v[188:191], v[56:59]
	v_mfma_f32_16x16x32_bf16 v[44:47], v[140:143], v[192:195], v[44:47]
	v_mfma_f32_16x16x32_bf16 v[44:47], v[150:153], v[196:199], v[44:47]
	v_mfma_f32_16x16x32_bf16 v[40:43], v[154:157], v[192:195], v[40:43]
	v_mfma_f32_16x16x32_bf16 v[40:43], v[158:161], v[196:199], v[40:43]
	v_mfma_f32_16x16x32_bf16 v[28:31], v[140:143], v[200:203], v[28:31]
	v_mfma_f32_16x16x32_bf16 v[28:31], v[150:153], v[204:207], v[28:31]
	v_mfma_f32_16x16x32_bf16 v[24:27], v[154:157], v[200:203], v[24:27]
	v_mfma_f32_16x16x32_bf16 v[24:27], v[158:161], v[204:207], v[24:27]
	v_mfma_f32_16x16x32_bf16 v[12:15], v[140:143], v[208:211], v[12:15]
	v_mfma_f32_16x16x32_bf16 v[12:15], v[150:153], v[212:215], v[12:15]
	v_mfma_f32_16x16x32_bf16 v[8:11], v[154:157], v[208:211], v[8:11]
	v_mfma_f32_16x16x32_bf16 v[8:11], v[158:161], v[212:215], v[8:11]
	v_mfma_f32_16x16x32_bf16 v[52:55], v[162:165], v[184:187], v[52:55]
	v_mfma_f32_16x16x32_bf16 v[52:55], v[166:169], v[188:191], v[52:55]
	v_mfma_f32_16x16x32_bf16 v[48:51], v[170:173], v[184:187], v[48:51]
	v_mfma_f32_16x16x32_bf16 v[48:51], v[174:177], v[188:191], v[48:51]
	v_mfma_f32_16x16x32_bf16 v[36:39], v[162:165], v[192:195], v[36:39]
	v_mfma_f32_16x16x32_bf16 v[36:39], v[166:169], v[196:199], v[36:39]
	v_mfma_f32_16x16x32_bf16 v[32:35], v[170:173], v[192:195], v[32:35]
	v_mfma_f32_16x16x32_bf16 v[32:35], v[174:177], v[196:199], v[32:35]
	v_mfma_f32_16x16x32_bf16 v[20:23], v[162:165], v[200:203], v[20:23]
	v_mfma_f32_16x16x32_bf16 v[20:23], v[166:169], v[204:207], v[20:23]
	v_mfma_f32_16x16x32_bf16 v[16:19], v[170:173], v[200:203], v[16:19]
	v_mfma_f32_16x16x32_bf16 v[16:19], v[174:177], v[204:207], v[16:19]
	v_mfma_f32_16x16x32_bf16 v[4:7], v[162:165], v[208:211], v[4:7]
	v_mfma_f32_16x16x32_bf16 v[4:7], v[166:169], v[212:215], v[4:7]
	s_barrier
	v_mfma_f32_16x16x32_bf16 v[0:3], v[170:173], v[208:211], v[0:3]
	v_mfma_f32_16x16x32_bf16 v[0:3], v[174:177], v[212:215], v[0:3]
	s_setprio 0
	s_add_i32 s76, s76, 2
	s_add_u32 s52, s52, 0x100
	s_addc_u32 s53, s53, 0
	s_add_u32 s74, s74, 0x100
	s_addc_u32 s75, s75, 0
	s_cmp_gt_u32 s76, 13
	s_cbranch_scc0 .LBB0_951
	s_and_b64 vcc, s[16:17], s[10:11]
	s_and_b64 vcc, vcc, exec
	s_cbranch_vccnz .Lpre_7
	s_and_b64 vcc, exec, s[16:17]
	s_cbranch_vccz .LBB0_954
	s_barrier

.Lpre_11:
	s_mov_b32 s98, s65
	s_mov_b32 s100, s44
	s_mov_b32 s65, s16
	s_mov_b32 s44, s18
	s_mov_b64 s[48:49], s[36:37]
	s_mov_b64 s[46:47], s[30:31]
	s_add_i32 s59, s59, 1
	s_mul_i32 s8, s59, s21
	s_mul_hi_u32 s9, s59, s20
	s_add_i32 s9, s9, s8
	s_mul_i32 s8, s59, s20
	s_add_u32 s30, s8, s2
	s_addc_u32 s31, s9, s3
	v_cmp_gt_i64_e32 vcc, s[30:31], v[138:139]
	v_cmp_lt_i64_e64 s[8:9], s[30:31], v[136:137]
	s_cbranch_vccnz .LBB0_1433_pk11
	s_lshr_b32 s16, s30, 3
	s_and_b32 s18, s30, 7
	s_lshl_b32 s18, s18, 1
	s_cmp_ge_u32 s16, 0xb0
	s_cbranch_scc0 .Ldec_11_pk11
	s_sub_u32 s16, s16, 0xb0
	s_add_u32 s18, s18, 1

.LBB0_1433_pk11:
	s_ashr_i32 s19, s18, 31
	s_lshl_b64 s[30:31], s[18:19], 19
	s_add_u32 s30, s80, s30
	s_addc_u32 s31, s81, s31
	s_and_b64 s[36:37], s[8:9], exec
	s_cselect_b32 s19, s31, s47
	s_cselect_b32 s66, s30, s46
	s_ashr_i32 s17, s16, 31
	s_lshl_b64 s[36:37], s[16:17], 19
	s_add_u32 s36, s52, s36
	s_addc_u32 s37, s53, s37
	s_and_b64 s[50:51], s[8:9], exec
	s_cselect_b32 s17, s37, s49
	s_cselect_b32 s67, s36, s48
	s_add_u32 s46, s46, 0x40080
	s_addc_u32 s47, s47, 0
	s_add_u32 s68, s48, 0x100
	s_addc_u32 s69, s49, 0
	s_mov_b32 s70, -2
	ds_read_b128 v[140:143], v147
	ds_read_b128 v[150:153], v147 offset:1024
	ds_read_b128 v[154:157], v147 offset:2048
	ds_read_b128 v[158:161], v147 offset:3072
	ds_read_b128 v[162:165], v148
	ds_read_b128 v[166:169], v148 offset:1024
	ds_read_b128 v[170:173], v148 offset:2048
	ds_read_b128 v[174:177], v148 offset:3072
	s_add_u32 s48, s46, 0xfffc0080
	s_addc_u32 s49, s47, -1
	s_cmp_eq_u32 s70, 12
	s_cselect_b32 s51, s19, s49
	s_cselect_b32 s50, s66, s48
	s_cselect_b32 s49, s17, s69
	s_cselect_b32 s48, s67, s68
	v_lshl_add_u64 v[178:179], s[46:47], 0, v[132:133]
	s_add_i32 m0, s45, 0xc000
	ds_read_b128 v[184:187], v149
	ds_read_b128 v[188:191], v149 offset:1024
	ds_read_b128 v[192:195], v149 offset:2048
	ds_read_b128 v[196:199], v149 offset:3072
	ds_read_b128 v[200:203], v149 offset:4096
	ds_read_b128 v[204:207], v149 offset:5120
	ds_read_b128 v[208:211], v149 offset:6144
	ds_read_b128 v[212:215], v149 offset:7168
	global_load_lds_dwordx4 v[178:179], off
	v_lshl_add_u64 v[178:179], s[46:47], 0, v[134:135]
	s_add_i32 m0, s45, 0xe000
	s_nop 0
	global_load_lds_dwordx4 v[178:179], off
	s_barrier
	v_mul_f32_e32 v221, 0xbfb8aa3b, v124
	v_exp_f32_e32 v221, v221
	v_mul_f32_e32 v224, 0xbfb8aa3b, v125
	v_exp_f32_e32 v224, v224
	v_lshl_or_b32 v218, s98, 7, v146
	v_add_f32_e32 v221, 1.0, v221
	v_rcp_f32_e32 v221, v221
	v_lshl_add_u32 v220, s100, 8, v144
	v_ashrrev_i32_e32 v219, 31, v218
	v_mov_b64_e32 v[216:217], s[22:23]
	v_mul_f32_e32 v124, v124, v221
	v_mul_f32_e32 v120, v120, v124
	v_add_f32_e32 v124, 1.0, v224
	v_mul_f32_e32 v221, 0xbfb8aa3b, v126
	v_rcp_f32_e32 v124, v124
	v_exp_f32_e32 v221, v221
	v_mul_f32_e32 v224, 0xbfb8aa3b, v127
	v_exp_f32_e32 v224, v224
	v_mul_f32_e32 v124, v125, v124
	v_add_f32_e32 v125, 1.0, v221
	v_rcp_f32_e32 v125, v125
	v_add_f32_e32 v221, 1.0, v224
	v_rcp_f32_e32 v221, v221
	v_mul_f32_e32 v121, v121, v124
	v_mul_f32_e32 v124, v126, v125
	v_mul_f32_e32 v125, 0xbfb8aa3b, v116
	v_exp_f32_e32 v125, v125
	v_mul_f32_e32 v122, v122, v124
	v_mul_f32_e32 v124, v127, v221
	v_mul_f32_e32 v123, v123, v124
	v_cvt_pk_bf16_f32 v120, v120, v121
	v_cvt_pk_bf16_f32 v121, v122, v123
	v_add_f32_e32 v122, 1.0, v125
	v_rcp_f32_e32 v122, v122
	v_mul_f32_e32 v123, 0xbfb8aa3b, v117
	v_exp_f32_e32 v123, v123
	v_mad_i64_i32 v[222:223], vcc, v220, s64, v[216:217]
	v_lshlrev_b64 v[218:219], 1, v[218:219]
	v_lshl_add_u64 v[222:223], v[222:223], 0, v[218:219]
	v_mul_f32_e32 v116, v116, v122
	global_store_dwordx2 v[222:223], v[120:121], off
	v_mul_f32_e32 v112, v112, v116
	v_add_f32_e32 v116, 1.0, v123
	v_mul_f32_e32 v120, 0xbfb8aa3b, v118
	v_rcp_f32_e32 v116, v116
	v_exp_f32_e32 v120, v120
	v_mul_f32_e32 v121, 0xbfb8aa3b, v119
	v_exp_f32_e32 v121, v121
	v_mul_f32_e32 v116, v117, v116
	v_add_f32_e32 v117, 1.0, v120
	v_rcp_f32_e32 v117, v117
	v_add_f32_e32 v120, 1.0, v121
	v_rcp_f32_e32 v120, v120
	v_mul_f32_e32 v113, v113, v116
	v_mul_f32_e32 v116, v118, v117
	v_mul_f32_e32 v114, v114, v116
	v_mul_f32_e32 v116, v119, v120
	v_cvt_pk_bf16_f32 v112, v112, v113
	v_mul_f32_e32 v115, v115, v116
	v_cvt_pk_bf16_f32 v113, v114, v115
	global_store_dwordx2 v[222:223], v[112:113], off offset:128
	v_mul_f32_e32 v112, 0xbfb8aa3b, v108
	v_exp_f32_e32 v114, v112
	v_mul_f32_e32 v115, 0xbfb8aa3b, v109
	v_exp_f32_e32 v115, v115
	v_or_b32_e32 v112, 16, v220
	v_add_f32_e32 v114, 1.0, v114
	v_rcp_f32_e32 v114, v114
	v_mad_i64_i32 v[112:113], vcc, v112, s64, v[216:217]
	v_lshl_add_u64 v[112:113], v[112:113], 0, v[218:219]
	v_mul_f32_e32 v108, v108, v114
	v_mul_f32_e32 v104, v104, v108
	v_add_f32_e32 v108, 1.0, v115
	v_mul_f32_e32 v114, 0xbfb8aa3b, v110
	v_rcp_f32_e32 v108, v108
	v_exp_f32_e32 v114, v114
	v_mul_f32_e32 v115, 0xbfb8aa3b, v111
	v_exp_f32_e32 v115, v115
	v_mul_f32_e32 v108, v109, v108
	v_add_f32_e32 v109, 1.0, v114
	v_rcp_f32_e32 v109, v109
	v_add_f32_e32 v114, 1.0, v115
	v_rcp_f32_e32 v114, v114
	v_mul_f32_e32 v105, v105, v108
	v_mul_f32_e32 v108, v110, v109
	v_mul_f32_e32 v109, 0xbfb8aa3b, v100
	v_exp_f32_e32 v109, v109
	v_mul_f32_e32 v106, v106, v108
	v_mul_f32_e32 v108, v111, v114
	v_mul_f32_e32 v107, v107, v108
	v_cvt_pk_bf16_f32 v104, v104, v105
	v_cvt_pk_bf16_f32 v105, v106, v107
	v_add_f32_e32 v106, 1.0, v109
	v_rcp_f32_e32 v106, v106
	v_mul_f32_e32 v107, 0xbfb8aa3b, v101
	v_exp_f32_e32 v107, v107
	global_store_dwordx2 v[112:113], v[104:105], off
	v_mul_f32_e32 v100, v100, v106
	v_mul_f32_e32 v96, v96, v100
	v_add_f32_e32 v100, 1.0, v107
	v_mul_f32_e32 v104, 0xbfb8aa3b, v102
	v_rcp_f32_e32 v100, v100
	v_exp_f32_e32 v104, v104
	v_mul_f32_e32 v105, 0xbfb8aa3b, v103
	v_exp_f32_e32 v105, v105
	v_mul_f32_e32 v100, v101, v100
	v_add_f32_e32 v101, 1.0, v104
	v_rcp_f32_e32 v101, v101
	v_add_f32_e32 v104, 1.0, v105
	v_rcp_f32_e32 v104, v104
	v_mul_f32_e32 v97, v97, v100
	v_mul_f32_e32 v100, v102, v101
	v_mul_f32_e32 v98, v98, v100
	v_mul_f32_e32 v100, v103, v104
	v_cvt_pk_bf16_f32 v96, v96, v97
	v_mul_f32_e32 v99, v99, v100
	v_cvt_pk_bf16_f32 v97, v98, v99
	global_store_dwordx2 v[112:113], v[96:97], off offset:128
	v_mul_f32_e32 v96, 0xbfb8aa3b, v92
	v_exp_f32_e32 v98, v96
	v_mul_f32_e32 v99, 0xbfb8aa3b, v93
	v_exp_f32_e32 v99, v99
	v_or_b32_e32 v96, 32, v220
	v_add_f32_e32 v98, 1.0, v98
	v_rcp_f32_e32 v98, v98
	v_mad_i64_i32 v[96:97], vcc, v96, s64, v[216:217]
	v_lshl_add_u64 v[96:97], v[96:97], 0, v[218:219]
	v_mul_f32_e32 v92, v92, v98
	v_mul_f32_e32 v88, v88, v92
	v_add_f32_e32 v92, 1.0, v99
	v_mul_f32_e32 v98, 0xbfb8aa3b, v94
	v_rcp_f32_e32 v92, v92
	v_exp_f32_e32 v98, v98
	v_mul_f32_e32 v99, 0xbfb8aa3b, v95
	v_exp_f32_e32 v99, v99
	v_mul_f32_e32 v92, v93, v92
	v_add_f32_e32 v93, 1.0, v98
	v_rcp_f32_e32 v93, v93
	v_add_f32_e32 v98, 1.0, v99
	v_rcp_f32_e32 v98, v98
	v_mul_f32_e32 v89, v89, v92
	v_mul_f32_e32 v92, v94, v93
	v_mul_f32_e32 v93, 0xbfb8aa3b, v84
	v_exp_f32_e32 v93, v93
	v_mul_f32_e32 v90, v90, v92
	v_mul_f32_e32 v92, v95, v98
	v_mul_f32_e32 v91, v91, v92
	v_cvt_pk_bf16_f32 v88, v88, v89
	v_cvt_pk_bf16_f32 v89, v90, v91
	v_add_f32_e32 v90, 1.0, v93
	v_rcp_f32_e32 v90, v90
	v_mul_f32_e32 v91, 0xbfb8aa3b, v85
	v_exp_f32_e32 v91, v91
	global_store_dwordx2 v[96:97], v[88:89], off
	v_mul_f32_e32 v84, v84, v90
	v_mul_f32_e32 v80, v80, v84
	v_add_f32_e32 v84, 1.0, v91
	v_mul_f32_e32 v88, 0xbfb8aa3b, v86
	v_rcp_f32_e32 v84, v84
	v_exp_f32_e32 v88, v88
	v_mul_f32_e32 v89, 0xbfb8aa3b, v87
	v_exp_f32_e32 v89, v89
	v_mul_f32_e32 v84, v85, v84
	v_add_f32_e32 v85, 1.0, v88
	v_rcp_f32_e32 v85, v85
	v_add_f32_e32 v88, 1.0, v89
	v_rcp_f32_e32 v88, v88
	v_mul_f32_e32 v81, v81, v84
	v_mul_f32_e32 v84, v86, v85
	v_mul_f32_e32 v82, v82, v84
	v_mul_f32_e32 v84, v87, v88
	v_cvt_pk_bf16_f32 v80, v80, v81
	v_mul_f32_e32 v83, v83, v84
	v_cvt_pk_bf16_f32 v81, v82, v83
	global_store_dwordx2 v[96:97], v[80:81], off offset:128
	v_mul_f32_e32 v80, 0xbfb8aa3b, v76
	v_exp_f32_e32 v82, v80
	v_mul_f32_e32 v83, 0xbfb8aa3b, v77
	v_exp_f32_e32 v83, v83
	v_or_b32_e32 v80, 48, v220
	v_add_f32_e32 v82, 1.0, v82
	v_rcp_f32_e32 v82, v82
	v_mad_i64_i32 v[80:81], vcc, v80, s64, v[216:217]
	v_lshl_add_u64 v[80:81], v[80:81], 0, v[218:219]
	v_mul_f32_e32 v76, v76, v82
	v_mul_f32_e32 v72, v72, v76
	v_add_f32_e32 v76, 1.0, v83
	v_mul_f32_e32 v82, 0xbfb8aa3b, v78
	v_rcp_f32_e32 v76, v76
	v_exp_f32_e32 v82, v82
	v_mul_f32_e32 v83, 0xbfb8aa3b, v79
	v_exp_f32_e32 v83, v83
	v_mul_f32_e32 v76, v77, v76
	v_add_f32_e32 v77, 1.0, v82
	v_rcp_f32_e32 v77, v77
	v_add_f32_e32 v82, 1.0, v83
	v_rcp_f32_e32 v82, v82
	v_mul_f32_e32 v73, v73, v76
	v_mul_f32_e32 v76, v78, v77
	v_mul_f32_e32 v77, 0xbfb8aa3b, v68
	v_exp_f32_e32 v77, v77
	v_mul_f32_e32 v74, v74, v76
	v_mul_f32_e32 v76, v79, v82
	v_mul_f32_e32 v75, v75, v76
	v_cvt_pk_bf16_f32 v72, v72, v73
	v_cvt_pk_bf16_f32 v73, v74, v75
	v_add_f32_e32 v74, 1.0, v77
	v_rcp_f32_e32 v74, v74
	v_mul_f32_e32 v75, 0xbfb8aa3b, v69
	v_exp_f32_e32 v75, v75
	global_store_dwordx2 v[80:81], v[72:73], off
	v_mul_f32_e32 v68, v68, v74
	v_mul_f32_e32 v64, v64, v68
	v_add_f32_e32 v68, 1.0, v75
	v_mul_f32_e32 v72, 0xbfb8aa3b, v70
	v_rcp_f32_e32 v68, v68
	v_exp_f32_e32 v72, v72
	v_mul_f32_e32 v73, 0xbfb8aa3b, v71
	v_exp_f32_e32 v73, v73
	v_mul_f32_e32 v68, v69, v68
	v_add_f32_e32 v69, 1.0, v72
	v_rcp_f32_e32 v69, v69
	v_add_f32_e32 v72, 1.0, v73
	v_rcp_f32_e32 v72, v72
	v_mul_f32_e32 v65, v65, v68
	v_mul_f32_e32 v68, v70, v69
	v_mul_f32_e32 v66, v66, v68
	v_mul_f32_e32 v68, v71, v72
	v_cvt_pk_bf16_f32 v64, v64, v65
	v_mul_f32_e32 v67, v67, v68
	v_cvt_pk_bf16_f32 v65, v66, v67
	global_store_dwordx2 v[80:81], v[64:65], off offset:128
	v_mul_f32_e32 v64, 0xbfb8aa3b, v60
	v_exp_f32_e32 v66, v64
	v_mul_f32_e32 v67, 0xbfb8aa3b, v61
	v_exp_f32_e32 v67, v67
	v_add_u32_e32 v64, 0x80, v220
	v_add_f32_e32 v66, 1.0, v66
	v_rcp_f32_e32 v66, v66
	v_mad_i64_i32 v[64:65], vcc, v64, s64, v[216:217]
	v_lshl_add_u64 v[64:65], v[64:65], 0, v[218:219]
	v_mul_f32_e32 v60, v60, v66
	v_mul_f32_e32 v56, v56, v60
	v_add_f32_e32 v60, 1.0, v67
	v_mul_f32_e32 v66, 0xbfb8aa3b, v62
	v_rcp_f32_e32 v60, v60
	v_exp_f32_e32 v66, v66
	v_mul_f32_e32 v67, 0xbfb8aa3b, v63
	v_exp_f32_e32 v67, v67
	v_mul_f32_e32 v60, v61, v60
	v_add_f32_e32 v61, 1.0, v66
	v_rcp_f32_e32 v61, v61
	v_add_f32_e32 v66, 1.0, v67
	v_rcp_f32_e32 v66, v66
	v_mul_f32_e32 v57, v57, v60
	v_mul_f32_e32 v60, v62, v61
	v_mul_f32_e32 v61, 0xbfb8aa3b, v52
	v_exp_f32_e32 v61, v61
	v_mul_f32_e32 v58, v58, v60
	v_mul_f32_e32 v60, v63, v66
	v_mul_f32_e32 v59, v59, v60
	v_cvt_pk_bf16_f32 v56, v56, v57
	v_cvt_pk_bf16_f32 v57, v58, v59
	v_add_f32_e32 v58, 1.0, v61
	v_rcp_f32_e32 v58, v58
	v_mul_f32_e32 v59, 0xbfb8aa3b, v53
	v_exp_f32_e32 v59, v59
	global_store_dwordx2 v[64:65], v[56:57], off
	v_mul_f32_e32 v52, v52, v58
	v_mul_f32_e32 v48, v48, v52
	v_add_f32_e32 v52, 1.0, v59
	v_mul_f32_e32 v56, 0xbfb8aa3b, v54
	v_rcp_f32_e32 v52, v52
	v_exp_f32_e32 v56, v56
	v_mul_f32_e32 v57, 0xbfb8aa3b, v55
	v_exp_f32_e32 v57, v57
	v_mul_f32_e32 v52, v53, v52
	v_add_f32_e32 v53, 1.0, v56
	v_rcp_f32_e32 v53, v53
	v_add_f32_e32 v56, 1.0, v57
	v_rcp_f32_e32 v56, v56
	v_mul_f32_e32 v49, v49, v52
	v_mul_f32_e32 v52, v54, v53
	v_mul_f32_e32 v50, v50, v52
	v_mul_f32_e32 v52, v55, v56
	v_cvt_pk_bf16_f32 v48, v48, v49
	v_mul_f32_e32 v51, v51, v52
	v_cvt_pk_bf16_f32 v49, v50, v51
	global_store_dwordx2 v[64:65], v[48:49], off offset:128
	v_mul_f32_e32 v48, 0xbfb8aa3b, v44
	v_exp_f32_e32 v50, v48
	v_mul_f32_e32 v51, 0xbfb8aa3b, v45
	v_exp_f32_e32 v51, v51
	v_add_u32_e32 v48, 0x90, v220
	v_add_f32_e32 v50, 1.0, v50
	v_rcp_f32_e32 v50, v50
	v_mad_i64_i32 v[48:49], vcc, v48, s64, v[216:217]
	v_lshl_add_u64 v[48:49], v[48:49], 0, v[218:219]
	v_mul_f32_e32 v44, v44, v50
	v_mul_f32_e32 v40, v40, v44
	v_add_f32_e32 v44, 1.0, v51
	v_mul_f32_e32 v50, 0xbfb8aa3b, v46
	v_rcp_f32_e32 v44, v44
	v_exp_f32_e32 v50, v50
	v_mul_f32_e32 v51, 0xbfb8aa3b, v47
	v_exp_f32_e32 v51, v51
	v_mul_f32_e32 v44, v45, v44
	v_add_f32_e32 v45, 1.0, v50
	v_rcp_f32_e32 v45, v45
	v_add_f32_e32 v50, 1.0, v51
	v_rcp_f32_e32 v50, v50
	v_mul_f32_e32 v41, v41, v44
	v_mul_f32_e32 v44, v46, v45
	v_mul_f32_e32 v45, 0xbfb8aa3b, v36
	v_exp_f32_e32 v45, v45
	v_mul_f32_e32 v42, v42, v44
	v_mul_f32_e32 v44, v47, v50
	v_mul_f32_e32 v43, v43, v44
	v_cvt_pk_bf16_f32 v40, v40, v41
	v_cvt_pk_bf16_f32 v41, v42, v43
	v_add_f32_e32 v42, 1.0, v45
	v_rcp_f32_e32 v42, v42
	v_mul_f32_e32 v43, 0xbfb8aa3b, v37
	v_exp_f32_e32 v43, v43
	global_store_dwordx2 v[48:49], v[40:41], off
	v_mul_f32_e32 v36, v36, v42
	v_mul_f32_e32 v32, v32, v36
	v_add_f32_e32 v36, 1.0, v43
	v_mul_f32_e32 v40, 0xbfb8aa3b, v38
	v_rcp_f32_e32 v36, v36
	v_exp_f32_e32 v40, v40
	v_mul_f32_e32 v41, 0xbfb8aa3b, v39
	v_exp_f32_e32 v41, v41
	v_mul_f32_e32 v36, v37, v36
	v_add_f32_e32 v37, 1.0, v40
	v_rcp_f32_e32 v37, v37
	v_add_f32_e32 v40, 1.0, v41
	v_rcp_f32_e32 v40, v40
	v_mul_f32_e32 v33, v33, v36
	v_mul_f32_e32 v36, v38, v37
	v_mul_f32_e32 v34, v34, v36
	v_mul_f32_e32 v36, v39, v40
	v_cvt_pk_bf16_f32 v32, v32, v33
	v_mul_f32_e32 v35, v35, v36
	v_cvt_pk_bf16_f32 v33, v34, v35
	global_store_dwordx2 v[48:49], v[32:33], off offset:128
	v_mul_f32_e32 v32, 0xbfb8aa3b, v28
	v_exp_f32_e32 v34, v32
	v_mul_f32_e32 v35, 0xbfb8aa3b, v29
	v_exp_f32_e32 v35, v35
	v_add_u32_e32 v32, 0xa0, v220
	v_add_f32_e32 v34, 1.0, v34
	v_rcp_f32_e32 v34, v34
	v_mad_i64_i32 v[32:33], vcc, v32, s64, v[216:217]
	v_lshl_add_u64 v[32:33], v[32:33], 0, v[218:219]
	v_mul_f32_e32 v28, v28, v34
	v_mul_f32_e32 v24, v24, v28
	v_add_f32_e32 v28, 1.0, v35
	v_mul_f32_e32 v34, 0xbfb8aa3b, v30
	v_rcp_f32_e32 v28, v28
	v_exp_f32_e32 v34, v34
	v_mul_f32_e32 v35, 0xbfb8aa3b, v31
	v_exp_f32_e32 v35, v35
	v_mul_f32_e32 v28, v29, v28
	v_add_f32_e32 v29, 1.0, v34
	v_rcp_f32_e32 v29, v29
	v_add_f32_e32 v34, 1.0, v35
	v_rcp_f32_e32 v34, v34
	v_mul_f32_e32 v25, v25, v28
	v_mul_f32_e32 v28, v30, v29
	v_mul_f32_e32 v29, 0xbfb8aa3b, v20
	v_exp_f32_e32 v29, v29
	v_mul_f32_e32 v26, v26, v28
	v_mul_f32_e32 v28, v31, v34
	v_mul_f32_e32 v27, v27, v28
	v_cvt_pk_bf16_f32 v24, v24, v25
	v_cvt_pk_bf16_f32 v25, v26, v27
	v_add_f32_e32 v26, 1.0, v29
	v_rcp_f32_e32 v26, v26
	v_mul_f32_e32 v27, 0xbfb8aa3b, v21
	v_exp_f32_e32 v27, v27
	global_store_dwordx2 v[32:33], v[24:25], off
	v_mul_f32_e32 v20, v20, v26
	v_mul_f32_e32 v16, v16, v20
	v_add_f32_e32 v20, 1.0, v27
	v_mul_f32_e32 v24, 0xbfb8aa3b, v22
	v_rcp_f32_e32 v20, v20
	v_exp_f32_e32 v24, v24
	v_mul_f32_e32 v25, 0xbfb8aa3b, v23
	v_exp_f32_e32 v25, v25
	v_mul_f32_e32 v20, v21, v20
	v_add_f32_e32 v21, 1.0, v24
	v_rcp_f32_e32 v21, v21
	v_add_f32_e32 v24, 1.0, v25
	v_rcp_f32_e32 v24, v24
	v_mul_f32_e32 v17, v17, v20
	v_mul_f32_e32 v20, v22, v21
	v_mul_f32_e32 v18, v18, v20
	v_mul_f32_e32 v20, v23, v24
	v_cvt_pk_bf16_f32 v16, v16, v17
	v_mul_f32_e32 v19, v19, v20
	v_cvt_pk_bf16_f32 v17, v18, v19
	global_store_dwordx2 v[32:33], v[16:17], off offset:128
	v_mul_f32_e32 v16, 0xbfb8aa3b, v12
	v_exp_f32_e32 v18, v16
	v_mul_f32_e32 v19, 0xbfb8aa3b, v13
	v_exp_f32_e32 v19, v19
	v_add_u32_e32 v16, 0xb0, v220
	v_add_f32_e32 v18, 1.0, v18
	v_rcp_f32_e32 v18, v18
	v_mad_i64_i32 v[16:17], vcc, v16, s64, v[216:217]
	v_lshl_add_u64 v[16:17], v[16:17], 0, v[218:219]
	v_mul_f32_e32 v12, v12, v18
	v_mul_f32_e32 v8, v8, v12
	v_add_f32_e32 v12, 1.0, v19
	v_mul_f32_e32 v18, 0xbfb8aa3b, v14
	v_rcp_f32_e32 v12, v12
	v_exp_f32_e32 v18, v18
	v_mul_f32_e32 v19, 0xbfb8aa3b, v15
	v_exp_f32_e32 v19, v19
	v_mul_f32_e32 v12, v13, v12
	v_add_f32_e32 v13, 1.0, v18
	v_rcp_f32_e32 v13, v13
	v_add_f32_e32 v18, 1.0, v19
	v_rcp_f32_e32 v18, v18
	v_mul_f32_e32 v9, v9, v12
	v_mul_f32_e32 v12, v14, v13
	v_mul_f32_e32 v13, 0xbfb8aa3b, v4
	v_exp_f32_e32 v13, v13
	v_mul_f32_e32 v10, v10, v12
	v_mul_f32_e32 v12, v15, v18
	v_mul_f32_e32 v11, v11, v12
	v_cvt_pk_bf16_f32 v8, v8, v9
	v_cvt_pk_bf16_f32 v9, v10, v11
	v_add_f32_e32 v10, 1.0, v13
	v_rcp_f32_e32 v10, v10
	v_mul_f32_e32 v11, 0xbfb8aa3b, v5
	v_exp_f32_e32 v11, v11
	global_store_dwordx2 v[16:17], v[8:9], off
	v_mul_f32_e32 v4, v4, v10
	v_mul_f32_e32 v0, v0, v4
	v_add_f32_e32 v4, 1.0, v11
	v_mul_f32_e32 v8, 0xbfb8aa3b, v6
	v_rcp_f32_e32 v4, v4
	v_exp_f32_e32 v8, v8
	v_mul_f32_e32 v9, 0xbfb8aa3b, v7
	v_exp_f32_e32 v9, v9
	v_mul_f32_e32 v4, v5, v4
	v_add_f32_e32 v5, 1.0, v8
	v_rcp_f32_e32 v5, v5
	v_add_f32_e32 v8, 1.0, v9
	v_rcp_f32_e32 v8, v8
	v_mul_f32_e32 v1, v1, v4
	v_mul_f32_e32 v4, v6, v5
	v_mul_f32_e32 v2, v2, v4
	v_mul_f32_e32 v4, v7, v8
	v_mul_f32_e32 v3, v3, v4
	v_cvt_pk_bf16_f32 v0, v0, v1
	v_cvt_pk_bf16_f32 v1, v2, v3
	global_store_dwordx2 v[16:17], v[0:1], off offset:128
	s_waitcnt vmcnt(8)
	s_waitcnt lgkmcnt(0)
	s_barrier
	s_waitcnt lgkmcnt(0)
	v_mfma_f32_16x16x32_bf16 v[124:127], v[140:143], v[184:187], 0
	v_mfma_f32_16x16x32_bf16 v[124:127], v[150:153], v[188:191], v[124:127]
	s_setprio 1
	v_mfma_f32_16x16x32_bf16 v[120:123], v[154:157], v[184:187], 0
	v_mfma_f32_16x16x32_bf16 v[120:123], v[158:161], v[188:191], v[120:123]
	v_mfma_f32_16x16x32_bf16 v[108:111], v[140:143], v[192:195], 0
	v_mfma_f32_16x16x32_bf16 v[108:111], v[150:153], v[196:199], v[108:111]
	v_mfma_f32_16x16x32_bf16 v[104:107], v[154:157], v[192:195], 0
	v_mfma_f32_16x16x32_bf16 v[104:107], v[158:161], v[196:199], v[104:107]
	v_mfma_f32_16x16x32_bf16 v[92:95], v[140:143], v[200:203], 0
	v_mfma_f32_16x16x32_bf16 v[92:95], v[150:153], v[204:207], v[92:95]
	v_mfma_f32_16x16x32_bf16 v[88:91], v[154:157], v[200:203], 0
	v_mfma_f32_16x16x32_bf16 v[88:91], v[158:161], v[204:207], v[88:91]
	v_mfma_f32_16x16x32_bf16 v[76:79], v[140:143], v[208:211], 0
	v_mfma_f32_16x16x32_bf16 v[76:79], v[150:153], v[212:215], v[76:79]
	v_mfma_f32_16x16x32_bf16 v[72:75], v[154:157], v[208:211], 0
	v_mfma_f32_16x16x32_bf16 v[72:75], v[158:161], v[212:215], v[72:75]
	v_mfma_f32_16x16x32_bf16 v[116:119], v[162:165], v[184:187], 0
	v_mfma_f32_16x16x32_bf16 v[116:119], v[166:169], v[188:191], v[116:119]
	v_mfma_f32_16x16x32_bf16 v[112:115], v[170:173], v[184:187], 0
	v_mfma_f32_16x16x32_bf16 v[112:115], v[174:177], v[188:191], v[112:115]
	v_mfma_f32_16x16x32_bf16 v[100:103], v[162:165], v[192:195], 0
	v_mfma_f32_16x16x32_bf16 v[100:103], v[166:169], v[196:199], v[100:103]
	v_mfma_f32_16x16x32_bf16 v[96:99], v[170:173], v[192:195], 0
	v_mfma_f32_16x16x32_bf16 v[96:99], v[174:177], v[196:199], v[96:99]
	v_mfma_f32_16x16x32_bf16 v[84:87], v[162:165], v[200:203], 0
	v_mfma_f32_16x16x32_bf16 v[84:87], v[166:169], v[204:207], v[84:87]
	v_mfma_f32_16x16x32_bf16 v[80:83], v[170:173], v[200:203], 0
	v_mfma_f32_16x16x32_bf16 v[80:83], v[174:177], v[204:207], v[80:83]
	v_mfma_f32_16x16x32_bf16 v[68:71], v[162:165], v[208:211], 0
	v_mfma_f32_16x16x32_bf16 v[68:71], v[166:169], v[212:215], v[68:71]
	s_barrier
	v_mfma_f32_16x16x32_bf16 v[64:67], v[170:173], v[208:211], 0
	v_mfma_f32_16x16x32_bf16 v[64:67], v[174:177], v[212:215], v[64:67]
	s_setprio 0
	s_add_i32 s71, s62, s54
	v_lshl_add_u64 v[178:179], s[48:49], 0, v[130:131]
	s_mov_b32 m0, s71
	ds_read_b128 v[184:187], v149 offset:16384
	ds_read_b128 v[188:191], v149 offset:17408
	ds_read_b128 v[192:195], v149 offset:18432
	ds_read_b128 v[196:199], v149 offset:19456
	ds_read_b128 v[200:203], v149 offset:20480
	ds_read_b128 v[204:207], v149 offset:21504
	ds_read_b128 v[208:211], v149 offset:22528
	ds_read_b128 v[212:215], v149 offset:23552
	global_load_lds_dwordx4 v[178:179], off
	s_add_i32 m0, s71, 0x2000
	s_add_u32 s72, s48, 0x40000
	v_lshl_add_u64 v[216:217], s[48:49], 0, v[128:129]
	s_addc_u32 s73, s49, 0
	s_add_i32 s71, s63, s54
	global_load_lds_dwordx4 v[216:217], off
	v_lshl_add_u64 v[218:219], s[72:73], 0, v[130:131]
	s_mov_b32 m0, s71
	v_lshl_add_u64 v[220:221], s[50:51], 0, v[128:129]
	global_load_lds_dwordx4 v[218:219], off
	v_lshl_add_u64 v[218:219], s[72:73], 0, v[128:129]
	s_add_i32 m0, s71, 0x2000
	s_nop 0
	global_load_lds_dwordx4 v[218:219], off
	v_lshl_add_u64 v[218:219], s[50:51], 0, v[130:131]
	s_mov_b32 m0, s45
	s_nop 0
	global_load_lds_dwordx4 v[218:219], off
	s_mov_b32 m0, s56
	s_nop 0
	global_load_lds_dwordx4 v[220:221], off
	s_waitcnt vmcnt(8)
	s_waitcnt lgkmcnt(0)
	s_barrier
	s_waitcnt lgkmcnt(0)
	v_mfma_f32_16x16x32_bf16 v[60:63], v[140:143], v[184:187], 0
	v_mfma_f32_16x16x32_bf16 v[60:63], v[150:153], v[188:191], v[60:63]
	s_setprio 1
	v_mfma_f32_16x16x32_bf16 v[56:59], v[154:157], v[184:187], 0
	v_mfma_f32_16x16x32_bf16 v[56:59], v[158:161], v[188:191], v[56:59]
	v_mfma_f32_16x16x32_bf16 v[44:47], v[140:143], v[192:195], 0
	v_mfma_f32_16x16x32_bf16 v[44:47], v[150:153], v[196:199], v[44:47]
	v_mfma_f32_16x16x32_bf16 v[40:43], v[154:157], v[192:195], 0
	v_mfma_f32_16x16x32_bf16 v[40:43], v[158:161], v[196:199], v[40:43]
	v_mfma_f32_16x16x32_bf16 v[28:31], v[140:143], v[200:203], 0
	v_mfma_f32_16x16x32_bf16 v[28:31], v[150:153], v[204:207], v[28:31]
	v_mfma_f32_16x16x32_bf16 v[24:27], v[154:157], v[200:203], 0
	v_mfma_f32_16x16x32_bf16 v[24:27], v[158:161], v[204:207], v[24:27]
	v_mfma_f32_16x16x32_bf16 v[12:15], v[140:143], v[208:211], 0
	v_mfma_f32_16x16x32_bf16 v[12:15], v[150:153], v[212:215], v[12:15]
	v_mfma_f32_16x16x32_bf16 v[8:11], v[154:157], v[208:211], 0
	v_mfma_f32_16x16x32_bf16 v[8:11], v[158:161], v[212:215], v[8:11]
	v_mfma_f32_16x16x32_bf16 v[52:55], v[162:165], v[184:187], 0
	v_mfma_f32_16x16x32_bf16 v[52:55], v[166:169], v[188:191], v[52:55]
	v_mfma_f32_16x16x32_bf16 v[48:51], v[170:173], v[184:187], 0
	v_mfma_f32_16x16x32_bf16 v[48:51], v[174:177], v[188:191], v[48:51]
	v_mfma_f32_16x16x32_bf16 v[36:39], v[162:165], v[192:195], 0
	v_mfma_f32_16x16x32_bf16 v[36:39], v[166:169], v[196:199], v[36:39]
	v_mfma_f32_16x16x32_bf16 v[32:35], v[170:173], v[192:195], 0
	v_mfma_f32_16x16x32_bf16 v[32:35], v[174:177], v[196:199], v[32:35]
	v_mfma_f32_16x16x32_bf16 v[20:23], v[162:165], v[200:203], 0
	v_mfma_f32_16x16x32_bf16 v[20:23], v[166:169], v[204:207], v[20:23]
	v_mfma_f32_16x16x32_bf16 v[16:19], v[170:173], v[200:203], 0
	v_mfma_f32_16x16x32_bf16 v[16:19], v[174:177], v[204:207], v[16:19]
	v_mfma_f32_16x16x32_bf16 v[4:7], v[162:165], v[208:211], 0
	v_mfma_f32_16x16x32_bf16 v[4:7], v[166:169], v[212:215], v[4:7]
	s_barrier
	v_mfma_f32_16x16x32_bf16 v[0:3], v[170:173], v[208:211], 0
	v_mfma_f32_16x16x32_bf16 v[0:3], v[174:177], v[212:215], v[0:3]
	s_setprio 0
	s_branch .Lmid_gemm11

.Lmid_gemm11:
	s_add_i32 s71, 0, 0x18000
	s_add_i32 s72, 0, 0x1c000
	v_add_u32_e32 v158, s71, v145
	v_add_u32_e32 v174, s72, v145
	ds_read_b128 v[140:143], v158
	ds_read_b128 v[150:153], v158 offset:1024
	ds_read_b128 v[154:157], v158 offset:2048
	ds_read_b128 v[158:161], v158 offset:3072
	ds_read_b128 v[162:165], v174
	ds_read_b128 v[166:169], v174 offset:1024
	ds_read_b128 v[170:173], v174 offset:2048
	ds_read_b128 v[174:177], v174 offset:3072
	s_add_u32 s50, s50, 0x40000
	s_addc_u32 s51, s51, 0
	s_mov_b32 m0, s57
	v_lshl_add_u64 v[222:223], s[50:51], 0, v[130:131]
	ds_read_b128 v[184:187], v149 offset:32768
	ds_read_b128 v[188:191], v149 offset:33792
	ds_read_b128 v[192:195], v149 offset:34816
	ds_read_b128 v[196:199], v149 offset:35840
	ds_read_b128 v[200:203], v149 offset:36864
	ds_read_b128 v[204:207], v149 offset:37888
	ds_read_b128 v[208:211], v149 offset:38912
	ds_read_b128 v[212:215], v149 offset:39936
	global_load_lds_dwordx4 v[222:223], off
	v_lshl_add_u64 v[222:223], s[50:51], 0, v[128:129]
	s_mov_b32 m0, s58
	s_nop 0
	global_load_lds_dwordx4 v[222:223], off
	s_waitcnt vmcnt(8)
	s_waitcnt lgkmcnt(0)
	s_barrier
	s_waitcnt lgkmcnt(0)
	v_mfma_f32_16x16x32_bf16 v[124:127], v[140:143], v[184:187], v[124:127]
	v_mfma_f32_16x16x32_bf16 v[124:127], v[150:153], v[188:191], v[124:127]
	s_setprio 1
	v_mfma_f32_16x16x32_bf16 v[120:123], v[154:157], v[184:187], v[120:123]
	v_mfma_f32_16x16x32_bf16 v[120:123], v[158:161], v[188:191], v[120:123]
	v_mfma_f32_16x16x32_bf16 v[108:111], v[140:143], v[192:195], v[108:111]
	v_mfma_f32_16x16x32_bf16 v[108:111], v[150:153], v[196:199], v[108:111]
	v_mfma_f32_16x16x32_bf16 v[104:107], v[154:157], v[192:195], v[104:107]
	v_mfma_f32_16x16x32_bf16 v[104:107], v[158:161], v[196:199], v[104:107]
	v_mfma_f32_16x16x32_bf16 v[92:95], v[140:143], v[200:203], v[92:95]
	v_mfma_f32_16x16x32_bf16 v[92:95], v[150:153], v[204:207], v[92:95]
	v_mfma_f32_16x16x32_bf16 v[88:91], v[154:157], v[200:203], v[88:91]
	v_mfma_f32_16x16x32_bf16 v[88:91], v[158:161], v[204:207], v[88:91]
	v_mfma_f32_16x16x32_bf16 v[76:79], v[140:143], v[208:211], v[76:79]
	v_mfma_f32_16x16x32_bf16 v[76:79], v[150:153], v[212:215], v[76:79]
	v_mfma_f32_16x16x32_bf16 v[72:75], v[154:157], v[208:211], v[72:75]
	v_mfma_f32_16x16x32_bf16 v[72:75], v[158:161], v[212:215], v[72:75]
	v_mfma_f32_16x16x32_bf16 v[116:119], v[162:165], v[184:187], v[116:119]
	v_mfma_f32_16x16x32_bf16 v[116:119], v[166:169], v[188:191], v[116:119]
	v_mfma_f32_16x16x32_bf16 v[112:115], v[170:173], v[184:187], v[112:115]
	v_mfma_f32_16x16x32_bf16 v[112:115], v[174:177], v[188:191], v[112:115]
	v_mfma_f32_16x16x32_bf16 v[100:103], v[162:165], v[192:195], v[100:103]
	v_mfma_f32_16x16x32_bf16 v[100:103], v[166:169], v[196:199], v[100:103]
	v_mfma_f32_16x16x32_bf16 v[96:99], v[170:173], v[192:195], v[96:99]
	v_mfma_f32_16x16x32_bf16 v[96:99], v[174:177], v[196:199], v[96:99]
	v_mfma_f32_16x16x32_bf16 v[84:87], v[162:165], v[200:203], v[84:87]
	v_mfma_f32_16x16x32_bf16 v[84:87], v[166:169], v[204:207], v[84:87]
	v_mfma_f32_16x16x32_bf16 v[80:83], v[170:173], v[200:203], v[80:83]
	v_mfma_f32_16x16x32_bf16 v[80:83], v[174:177], v[204:207], v[80:83]
	v_mfma_f32_16x16x32_bf16 v[68:71], v[162:165], v[208:211], v[68:71]
	v_mfma_f32_16x16x32_bf16 v[68:71], v[166:169], v[212:215], v[68:71]
	s_barrier
	v_mfma_f32_16x16x32_bf16 v[64:67], v[170:173], v[208:211], v[64:67]
	v_mfma_f32_16x16x32_bf16 v[64:67], v[174:177], v[212:215], v[64:67]
	s_setprio 0
	s_add_i32 s50, s71, s54
	v_lshl_add_u64 v[178:179], v[178:179], 0, s[10:11]
	s_mov_b32 m0, s50
	ds_read_b128 v[184:187], v149 offset:49152
	ds_read_b128 v[188:191], v149 offset:50176
	ds_read_b128 v[192:195], v149 offset:51200
	ds_read_b128 v[196:199], v149 offset:52224
	ds_read_b128 v[200:203], v149 offset:53248
	ds_read_b128 v[204:207], v149 offset:54272
	ds_read_b128 v[208:211], v149 offset:55296
	ds_read_b128 v[212:215], v149 offset:56320
	global_load_lds_dwordx4 v[178:179], off
	s_add_i32 m0, s50, 0x2000
	s_add_u32 s48, s48, 0x40080
	v_lshl_add_u64 v[178:179], v[216:217], 0, s[10:11]
	s_addc_u32 s49, s49, 0
	s_add_i32 s50, s72, s54
	global_load_lds_dwordx4 v[178:179], off
	v_lshl_add_u64 v[178:179], s[48:49], 0, v[130:131]
	s_mov_b32 m0, s50
	s_nop 0
	global_load_lds_dwordx4 v[178:179], off
	v_lshl_add_u64 v[178:179], s[48:49], 0, v[128:129]
	s_add_i32 m0, s50, 0x2000
	s_nop 0
	global_load_lds_dwordx4 v[178:179], off
	v_lshl_add_u64 v[178:179], v[218:219], 0, s[10:11]
	s_mov_b32 m0, s60
	s_nop 0
	global_load_lds_dwordx4 v[178:179], off
	v_lshl_add_u64 v[178:179], v[220:221], 0, s[10:11]
	s_mov_b32 m0, s61
	s_nop 0
	global_load_lds_dwordx4 v[178:179], off
	s_waitcnt vmcnt(8)
	s_waitcnt lgkmcnt(0)
	s_barrier
	s_waitcnt lgkmcnt(0)
	v_mfma_f32_16x16x32_bf16 v[60:63], v[140:143], v[184:187], v[60:63]
	v_mfma_f32_16x16x32_bf16 v[60:63], v[150:153], v[188:191], v[60:63]
	s_setprio 1
	v_mfma_f32_16x16x32_bf16 v[56:59], v[154:157], v[184:187], v[56:59]
	v_mfma_f32_16x16x32_bf16 v[56:59], v[158:161], v[188:191], v[56:59]
	v_mfma_f32_16x16x32_bf16 v[44:47], v[140:143], v[192:195], v[44:47]
	v_mfma_f32_16x16x32_bf16 v[44:47], v[150:153], v[196:199], v[44:47]
	v_mfma_f32_16x16x32_bf16 v[40:43], v[154:157], v[192:195], v[40:43]
	v_mfma_f32_16x16x32_bf16 v[40:43], v[158:161], v[196:199], v[40:43]
	v_mfma_f32_16x16x32_bf16 v[28:31], v[140:143], v[200:203], v[28:31]
	v_mfma_f32_16x16x32_bf16 v[28:31], v[150:153], v[204:207], v[28:31]
	v_mfma_f32_16x16x32_bf16 v[24:27], v[154:157], v[200:203], v[24:27]
	v_mfma_f32_16x16x32_bf16 v[24:27], v[158:161], v[204:207], v[24:27]
	v_mfma_f32_16x16x32_bf16 v[12:15], v[140:143], v[208:211], v[12:15]
	v_mfma_f32_16x16x32_bf16 v[12:15], v[150:153], v[212:215], v[12:15]
	v_mfma_f32_16x16x32_bf16 v[8:11], v[154:157], v[208:211], v[8:11]
	v_mfma_f32_16x16x32_bf16 v[8:11], v[158:161], v[212:215], v[8:11]
	v_mfma_f32_16x16x32_bf16 v[52:55], v[162:165], v[184:187], v[52:55]
	v_mfma_f32_16x16x32_bf16 v[52:55], v[166:169], v[188:191], v[52:55]
	v_mfma_f32_16x16x32_bf16 v[48:51], v[170:173], v[184:187], v[48:51]
	v_mfma_f32_16x16x32_bf16 v[48:51], v[174:177], v[188:191], v[48:51]
	v_mfma_f32_16x16x32_bf16 v[36:39], v[162:165], v[192:195], v[36:39]
	v_mfma_f32_16x16x32_bf16 v[36:39], v[166:169], v[196:199], v[36:39]
	v_mfma_f32_16x16x32_bf16 v[32:35], v[170:173], v[192:195], v[32:35]
	v_mfma_f32_16x16x32_bf16 v[32:35], v[174:177], v[196:199], v[32:35]
	v_mfma_f32_16x16x32_bf16 v[20:23], v[162:165], v[200:203], v[20:23]
	v_mfma_f32_16x16x32_bf16 v[20:23], v[166:169], v[204:207], v[20:23]
	v_mfma_f32_16x16x32_bf16 v[16:19], v[170:173], v[200:203], v[16:19]
	v_mfma_f32_16x16x32_bf16 v[16:19], v[174:177], v[204:207], v[16:19]
	v_mfma_f32_16x16x32_bf16 v[4:7], v[162:165], v[208:211], v[4:7]
	v_mfma_f32_16x16x32_bf16 v[4:7], v[166:169], v[212:215], v[4:7]
	s_barrier
	v_mfma_f32_16x16x32_bf16 v[0:3], v[170:173], v[208:211], v[0:3]
	v_mfma_f32_16x16x32_bf16 v[0:3], v[174:177], v[212:215], v[0:3]
	s_setprio 0
	s_add_i32 s70, s70, 2
	s_add_u32 s46, s46, 0x100
	s_addc_u32 s47, s47, 0
	s_add_u32 s68, s68, 0x100
	s_addc_u32 s69, s69, 0
	s_cmp_gt_u32 s70, 13
	s_cbranch_scc0 .LBB0_1434
	s_and_b64 vcc, s[12:13], s[8:9]
	s_and_b64 vcc, vcc, exec
	s_cbranch_vccnz .Lpre_11
	s_and_b64 vcc, exec, s[12:13]
	s_cbranch_vccz .LBB0_1437
	s_barrier
